# single-pass int8 weight conversion: + bf16 copy of the mixer pool/lru columns fused in, empty absmax loop and its grid barrier skipped, default cache policy on the conversion loads
# speedup vs baseline: 1.0368x; 1.0169x over previous
.LBB0_10:
	s_or_b64 exec, exec, s[4:5]
	s_add_u32 s8, s34, 0x100000
	s_addc_u32 s9, s35, 0
	s_add_u32 s24, s34, 0x9100000
	s_addc_u32 s25, s35, 0
	s_add_u32 s92, s34, 0x9300000
	s_addc_u32 s93, s35, 0
	s_add_u32 s28, s34, 0xe700000
	s_addc_u32 s5, s35, 0
	s_add_u32 s68, s34, 0x5100000
	s_addc_u32 s69, s35, 0
	s_add_u32 s0, s34, 0x61400000
	s_addc_u32 s1, s35, 0
	s_add_u32 s64, s34, 0x40000
	s_addc_u32 s65, s35, 0
	s_add_u32 s26, s34, 0x60000
	v_writelane_b32 v254, s0, 11
	s_addc_u32 s27, s35, 0
	s_mov_b32 s4, s28
	v_writelane_b32 v254, s1, 12
	s_add_u32 s0, s34, 0x80000
	s_addc_u32 s1, s35, 0
	s_add_u32 s40, s34, 0xe0000
	s_addc_u32 s41, s35, 0
	v_writelane_b32 v254, s0, 13
	s_add_u32 s76, s34, 0x3f400000
	s_addc_u32 s77, s35, 0
	v_writelane_b32 v254, s1, 14
	s_lshr_b32 s1, s89, 6
	s_lshl_b32 s0, s23, 3
	v_writelane_b32 v254, s23, 15
	s_add_i32 s90, s0, s1
	s_lshl_b32 s0, s1, 14
	v_writelane_b32 v254, s1, 16
	s_add_i32 s0, s0, 0
	v_writelane_b32 v254, s0, 17
	s_lshl_b32 s42, s33, 3
	v_readlane_b32 s20, v254, 7
	v_readlane_b32 s21, v254, 8
	v_readlane_b32 s22, v254, 9
	v_readlane_b32 s23, v254, 10
	v_writelane_b32 v254, s4, 18
	s_lshl_b32 s44, s33, 9
	s_cmp_lt_i32 s20, 1
	v_writelane_b32 v254, s5, 19
	v_writelane_b32 v254, s89, 20
	s_cselect_b64 s[0:1], -1, 0
	s_cmp_gt_i32 s21, 0
	v_writelane_b32 v254, s91, 21
	s_cselect_b64 s[2:3], -1, 0
	v_writelane_b32 v254, s95, 22
	s_and_b64 s[0:1], s[0:1], s[2:3]
	v_writelane_b32 v254, s40, 23
	s_andn2_b64 vcc, exec, s[0:1]
	s_nop 0
	v_writelane_b32 v254, s41, 24
	s_cbranch_vccnz .LBB0_202
	v_mbcnt_lo_u32_b32 v134, -1, 0
	v_mbcnt_hi_u32_b32 v134, -1, v134
	s_cmpk_gt_i32 s90, 0x3cff
	v_lshlrev_b32_e32 v4, 2, v134
	s_branch .Lp0_after_colmax
	v_ashrrev_i32_e32 v5, 31, v4
	v_readlane_b32 s48, v255, 23
	v_lshlrev_b64 v[0:1], 2, v[4:5]
	v_readlane_b32 s0, v254, 13
	v_readlane_b32 s49, v255, 24
	v_readlane_b32 s50, v255, 25
	v_readlane_b32 s51, v255, 26
	v_readlane_b32 s52, v255, 27
	v_readlane_b32 s53, v255, 28
	v_readlane_b32 s54, v255, 29
	v_readlane_b32 s55, v255, 30
	v_readlane_b32 s56, v255, 31
	v_readlane_b32 s57, v255, 32
	v_readlane_b32 s58, v255, 33
	v_readlane_b32 s59, v255, 34
	v_readlane_b32 s60, v255, 35
	v_readlane_b32 s61, v255, 36
	v_readlane_b32 s62, v255, 37
	v_readlane_b32 s63, v255, 38
	v_readlane_b32 s1, v254, 14
	v_lshl_add_u64 v[2:3], s[52:53], 0, v[0:1]
	v_readlane_b32 s48, v255, 39
	v_lshl_add_u64 v[8:9], s[0:1], 0, v[0:1]
	s_mov_b64 s[0:1], 0x96000
	v_readlane_b32 s56, v255, 47
	v_readlane_b32 s57, v255, 48
	v_lshl_add_u64 v[14:15], v[2:3], 0, s[0:1]
	s_mov_b64 s[0:1], 0x40000
	v_lshl_add_u64 v[2:3], s[56:57], 0, v[0:1]
	v_readlane_b32 s49, v255, 40
	v_readlane_b32 s50, v255, 41
	v_readlane_b32 s51, v255, 42
	v_lshl_add_u64 v[16:17], v[2:3], 0, s[0:1]
	s_mov_b64 s[0:1], 0x142800
	v_lshl_add_u64 v[6:7], s[40:41], 0, v[0:1]
	v_lshl_add_u64 v[10:11], s[26:27], 0, v[0:1]
	v_lshl_add_u64 v[12:13], s[64:65], 0, v[0:1]
	v_lshl_add_u64 v[0:1], v[0:1], 0, s[0:1]
	s_mov_b32 s0, s42
	s_mov_b32 s6, s44
	v_readlane_b32 s36, v255, 55
	v_readlane_b32 s52, v255, 43
	v_readlane_b32 s53, v255, 44
	v_readlane_b32 s54, v255, 45
	v_readlane_b32 s55, v255, 46
	v_readlane_b32 s58, v255, 49
	v_readlane_b32 s59, v255, 50
	v_readlane_b32 s60, v255, 51
	v_readlane_b32 s61, v255, 52
	v_readlane_b32 s62, v255, 53
	v_readlane_b32 s63, v255, 54
	v_readlane_b32 s42, v255, 61
	v_readlane_b32 s43, v255, 62
	v_readlane_b32 s48, v254, 3
	v_readlane_b32 s49, v254, 4
	v_readlane_b32 s50, v254, 5
	v_readlane_b32 s51, v254, 6
	v_readlane_b32 s40, v255, 59
	v_readlane_b32 s41, v255, 60
	v_lshl_add_u64 v[18:19], s[42:43], 0, v[0:1]
	s_mov_b32 s42, s0
	v_readlane_b32 s48, v255, 7
	v_readlane_b32 s0, v254, 15
	v_readlane_b32 s1, v254, 16
	s_lshl_b32 s4, s90, 8
	s_add_i32 s15, s90, 0xffffd500
	v_readlane_b32 s44, v255, 63
	v_readlane_b32 s40, v254, 23
	v_readlane_b32 s60, v255, 19
	v_readlane_b32 s61, v255, 20
	s_lshl_b32 s0, s0, 11
	s_lshl_b32 s1, s1, 8
	s_add_i32 s2, s90, 0xcd00
	s_add_i32 s3, s4, 0xffcd0000
	s_lshl_b32 s14, s33, 11
	v_readlane_b32 s41, v254, 24
	s_mov_b32 s44, s6
	s_add_i32 s18, s90, 0xea80
	s_add_i32 s19, s4, 0xffea8000
	v_lshl_add_u64 v[20:21], s[60:61], 0, v[0:1]
	s_add_i32 s20, s0, s1
	s_mov_b32 s21, 0xfff6a000
	s_mov_b32 s22, 0xfffc0000
	s_mov_b32 s23, s90
	s_lshl_b32 s10, s15, 8
	s_mov_b32 s13, 0
	s_mov_b64 s[16:17], 0x158000
	v_readlane_b32 s37, v255, 56
	v_readlane_b32 s38, v255, 57
	v_readlane_b32 s39, v255, 58
	v_readlane_b32 s45, v254, 0
	v_readlane_b32 s46, v254, 1
	v_readlane_b32 s47, v254, 2
	v_readlane_b32 s49, v255, 8
	v_readlane_b32 s50, v255, 9
	v_readlane_b32 s51, v255, 10
	v_readlane_b32 s52, v255, 11
	v_readlane_b32 s53, v255, 12
	v_readlane_b32 s54, v255, 13
	v_readlane_b32 s55, v255, 14
	v_readlane_b32 s56, v255, 15
	v_readlane_b32 s57, v255, 16
	v_readlane_b32 s58, v255, 17
	v_readlane_b32 s59, v255, 18
	v_readlane_b32 s62, v255, 21
	v_readlane_b32 s63, v255, 22
	s_branch .LBB0_14

.Lp0_after_colmax:
	v_readlane_b32 s0, v254, 15
	s_lshl_b32 s21, s0, 9
	s_mov_b32 s14, s90
	s_cmpk_gt_i32 s90, 0x69ff
	s_waitcnt lgkmcnt(0)
	s_barrier
	s_cbranch_scc1 .LBB0_115
	v_mbcnt_lo_u32_b32 v135, -1, 0
	v_mbcnt_hi_u32_b32 v135, -1, v135
	v_lshrrev_b32_e32 v136, 2, v135
	v_and_b32_e32 v137, 3, v135
	v_lshlrev_b32_e32 v230, 4, v137
	v_lshlrev_b32_e32 v231, 15, v137
	v_lshl_add_u32 v231, v136, 3, v231
	v_readlane_b32 s62, v254, 17
	v_readlane_b32 s1, v254, 16
	v_readlane_b32 s72, v254, 15
	s_mov_b32 s74, 0x42fe0000
	s_mov_b32 s11, 0
	v_lshlrev_b32_e32 v139, 11, v137
	v_lshl_add_u32 v139, v136, 2, v139
	s_nop 1
	v_add_u32_e32 v139, s62, v139
	v_lshlrev_b32_e32 v174, 2, v135
	v_xor_b32_e32 v192, 0x10, v174
	v_xor_b32_e32 v193, 0x20, v174
	v_xor_b32_e32 v194, 0x40, v174
	v_xor_b32_e32 v195, 0x80, v174
	v_lshrrev_b32_e32 v175, 5, v135
	v_and_b32_e32 v176, 31, v135
	v_lshlrev_b32_e32 v212, 9, v175
	v_lshl_add_u32 v212, v176, 4, v212
	v_add_u32_e32 v212, s62, v212
	v_lshlrev_b32_e32 v213, 12, v175
	v_lshl_add_u32 v213, v176, 4, v213
	v_readlane_b32 s48, v255, 47
	v_readlane_b32 s49, v255, 48
	v_mul_u32_u24_e32 v138, 0x20000, v136
	v_lshl_add_u32 v138, v137, 4, v138
	s_mul_i32 s3, s1, 0x1000000
	s_nop 1
	s_add_u32 s48, s48, s3
	s_addc_u32 s49, s49, 0
	s_mov_b32 s0, s72
	s_cmp_ge_u32 s0, 0x200
	s_cbranch_scc1 .Lc16_gates_done
	s_lshl_b32 s3, s0, 6
	s_add_u32 s56, s48, s3
	s_addc_u32 s57, s49, 0
	global_load_dwordx4 v[6:9], v138, s[56:57]
	s_add_u32 s56, s56, 0x8000
	s_addc_u32 s57, s57, 0
	global_load_dwordx4 v[10:13], v138, s[56:57]
	s_add_u32 s56, s56, 0x8000
	s_addc_u32 s57, s57, 0
	global_load_dwordx4 v[14:17], v138, s[56:57]
	s_add_u32 s56, s56, 0x8000
	s_addc_u32 s57, s57, 0
	global_load_dwordx4 v[18:21], v138, s[56:57]
	s_add_u32 s56, s56, 0x1e8000
	s_addc_u32 s57, s57, 0
	global_load_dwordx4 v[22:25], v138, s[56:57]
	s_add_u32 s56, s56, 0x8000
	s_addc_u32 s57, s57, 0
	global_load_dwordx4 v[26:29], v138, s[56:57]
	s_add_u32 s56, s56, 0x8000
	s_addc_u32 s57, s57, 0
	global_load_dwordx4 v[30:33], v138, s[56:57]
	s_add_u32 s56, s56, 0x8000
	s_addc_u32 s57, s57, 0
	global_load_dwordx4 v[34:37], v138, s[56:57]
	s_add_u32 s56, s56, 0x1e8000
	s_addc_u32 s57, s57, 0
	global_load_dwordx4 v[38:41], v138, s[56:57]
	s_add_u32 s56, s56, 0x8000
	s_addc_u32 s57, s57, 0
	global_load_dwordx4 v[42:45], v138, s[56:57]
	s_add_u32 s56, s56, 0x8000
	s_addc_u32 s57, s57, 0
	global_load_dwordx4 v[46:49], v138, s[56:57]
	s_add_u32 s56, s56, 0x8000
	s_addc_u32 s57, s57, 0
	global_load_dwordx4 v[50:53], v138, s[56:57]
	s_add_u32 s56, s56, 0x1e8000
	s_addc_u32 s57, s57, 0
	global_load_dwordx4 v[54:57], v138, s[56:57]
	s_add_u32 s56, s56, 0x8000
	s_addc_u32 s57, s57, 0
	global_load_dwordx4 v[58:61], v138, s[56:57]
	s_add_u32 s56, s56, 0x8000
	s_addc_u32 s57, s57, 0
	global_load_dwordx4 v[62:65], v138, s[56:57]
	s_add_u32 s56, s56, 0x8000
	s_addc_u32 s57, s57, 0
	global_load_dwordx4 v[66:69], v138, s[56:57]
	s_add_u32 s56, s56, 0x1e8000
	s_addc_u32 s57, s57, 0
	global_load_dwordx4 v[70:73], v138, s[56:57]
	s_add_u32 s56, s56, 0x8000
	s_addc_u32 s57, s57, 0
	global_load_dwordx4 v[74:77], v138, s[56:57]
	s_add_u32 s56, s56, 0x8000
	s_addc_u32 s57, s57, 0
	global_load_dwordx4 v[78:81], v138, s[56:57]
	s_add_u32 s56, s56, 0x8000
	s_addc_u32 s57, s57, 0
	global_load_dwordx4 v[82:85], v138, s[56:57]
	s_add_u32 s56, s56, 0x1e8000
	s_addc_u32 s57, s57, 0
	global_load_dwordx4 v[86:89], v138, s[56:57]
	s_add_u32 s56, s56, 0x8000
	s_addc_u32 s57, s57, 0
	global_load_dwordx4 v[90:93], v138, s[56:57]
	s_add_u32 s56, s56, 0x8000
	s_addc_u32 s57, s57, 0
	global_load_dwordx4 v[94:97], v138, s[56:57]
	s_add_u32 s56, s56, 0x8000
	s_addc_u32 s57, s57, 0
	global_load_dwordx4 v[98:101], v138, s[56:57]
	s_add_u32 s56, s56, 0x1e8000
	s_addc_u32 s57, s57, 0
	global_load_dwordx4 v[102:105], v138, s[56:57]
	s_add_u32 s56, s56, 0x8000
	s_addc_u32 s57, s57, 0
	global_load_dwordx4 v[106:109], v138, s[56:57]
	s_add_u32 s56, s56, 0x8000
	s_addc_u32 s57, s57, 0
	global_load_dwordx4 v[110:113], v138, s[56:57]
	s_add_u32 s56, s56, 0x8000
	s_addc_u32 s57, s57, 0
	global_load_dwordx4 v[114:117], v138, s[56:57]
	s_add_u32 s56, s56, 0x1e8000
	s_addc_u32 s57, s57, 0
	global_load_dwordx4 v[118:121], v138, s[56:57]
	s_add_u32 s56, s56, 0x8000
	s_addc_u32 s57, s57, 0
	global_load_dwordx4 v[122:125], v138, s[56:57]
	s_add_u32 s56, s56, 0x8000
	s_addc_u32 s57, s57, 0
	global_load_dwordx4 v[126:129], v138, s[56:57]
	s_add_u32 s56, s56, 0x8000
	s_addc_u32 s57, s57, 0
	global_load_dwordx4 v[130:133], v138, s[56:57]

.Lc16_gates_nocm:
	v_div_scale_f32 v175, s[70:71], v220, v220, s74
	v_rcp_f32_e32 v176, v175
	s_nop 0
	v_fma_f32 v177, -v175, v176, 1.0
	v_fmac_f32_e32 v176, v177, v176
	v_div_scale_f32 v177, vcc, s74, v220, s74
	v_mul_f32_e32 v178, v177, v176
	v_fma_f32 v180, -v175, v178, v177
	v_fmac_f32_e32 v178, v180, v176
	v_fma_f32 v175, -v175, v178, v177
	s_nop 0
	v_div_fmas_f32 v175, v175, v176, v178
	v_div_fixup_f32 v175, v175, v220, s74
	v_cmp_lt_f32_e32 vcc, 0, v220
	s_nop 1
	v_cndmask_b32_e32 v226, 0, v175, vcc
	v_div_scale_f32 v175, s[70:71], v221, v221, s74
	v_rcp_f32_e32 v176, v175
	s_nop 0
	v_fma_f32 v177, -v175, v176, 1.0
	v_fmac_f32_e32 v176, v177, v176
	v_div_scale_f32 v177, vcc, s74, v221, s74
	v_mul_f32_e32 v178, v177, v176
	v_fma_f32 v180, -v175, v178, v177
	v_fmac_f32_e32 v178, v180, v176
	v_fma_f32 v175, -v175, v178, v177
	s_nop 0
	v_div_fmas_f32 v175, v175, v176, v178
	v_div_fixup_f32 v175, v175, v221, s74
	v_cmp_lt_f32_e32 vcc, 0, v221
	s_nop 1
	v_cndmask_b32_e32 v227, 0, v175, vcc
	v_div_scale_f32 v175, s[70:71], v222, v222, s74
	v_rcp_f32_e32 v176, v175
	s_nop 0
	v_fma_f32 v177, -v175, v176, 1.0
	v_fmac_f32_e32 v176, v177, v176
	v_div_scale_f32 v177, vcc, s74, v222, s74
	v_mul_f32_e32 v178, v177, v176
	v_fma_f32 v180, -v175, v178, v177
	v_fmac_f32_e32 v178, v180, v176
	v_fma_f32 v175, -v175, v178, v177
	s_nop 0
	v_div_fmas_f32 v175, v175, v176, v178
	v_div_fixup_f32 v175, v175, v222, s74
	v_cmp_lt_f32_e32 vcc, 0, v222
	s_nop 1
	v_cndmask_b32_e32 v228, 0, v175, vcc
	v_div_scale_f32 v175, s[70:71], v223, v223, s74
	v_rcp_f32_e32 v176, v175
	s_nop 0
	v_fma_f32 v177, -v175, v176, 1.0
	v_fmac_f32_e32 v176, v177, v176
	v_div_scale_f32 v177, vcc, s74, v223, s74
	v_mul_f32_e32 v178, v177, v176
	v_fma_f32 v180, -v175, v178, v177
	v_fmac_f32_e32 v178, v180, v176
	v_fma_f32 v175, -v175, v178, v177
	s_nop 0
	v_div_fmas_f32 v175, v175, v176, v178
	v_div_fixup_f32 v175, v175, v223, s74
	v_cmp_lt_f32_e32 vcc, 0, v223
	s_nop 1
	v_cndmask_b32_e32 v229, 0, v175, vcc
	s_add_u32 s10, s0, s33
	s_lshl_b32 s3, s10, 6
	s_add_u32 s56, s48, s3
	s_addc_u32 s57, s49, 0
	v_mul_f32_e32 v186, v6, v226
	v_rndne_f32_e32 v186, v186
	v_cvt_i32_f32_e32 v186, v186
	v_mul_f32_e32 v187, v10, v226
	v_rndne_f32_e32 v187, v187
	v_cvt_i32_f32_e32 v187, v187
	v_mul_f32_e32 v188, v14, v226
	v_rndne_f32_e32 v188, v188
	v_cvt_i32_f32_e32 v188, v188
	v_mul_f32_e32 v189, v18, v226
	v_rndne_f32_e32 v189, v189
	v_cvt_i32_f32_e32 v189, v189
	v_and_b32_e32 v186, 0xff, v186
	v_and_b32_e32 v187, 0xff, v187
	v_and_b32_e32 v188, 0xff, v188
	v_lshl_or_b32 v190, v187, 8, v186
	v_lshl_or_b32 v190, v188, 16, v190
	v_lshl_or_b32 v190, v189, 24, v190
	ds_write_b32 v139, v190 offset:0
	v_mul_f32_e32 v186, v7, v227
	v_rndne_f32_e32 v186, v186
	v_cvt_i32_f32_e32 v186, v186
	v_mul_f32_e32 v187, v11, v227
	v_rndne_f32_e32 v187, v187
	v_cvt_i32_f32_e32 v187, v187
	v_mul_f32_e32 v188, v15, v227
	v_rndne_f32_e32 v188, v188
	v_cvt_i32_f32_e32 v188, v188
	v_mul_f32_e32 v189, v19, v227
	v_rndne_f32_e32 v189, v189
	v_cvt_i32_f32_e32 v189, v189
	v_and_b32_e32 v186, 0xff, v186
	v_and_b32_e32 v187, 0xff, v187
	v_and_b32_e32 v188, 0xff, v188
	v_lshl_or_b32 v190, v187, 8, v186
	v_lshl_or_b32 v190, v188, 16, v190
	v_lshl_or_b32 v190, v189, 24, v190
	ds_write_b32 v139, v190 offset:512
	v_mul_f32_e32 v186, v8, v228
	v_rndne_f32_e32 v186, v186
	v_cvt_i32_f32_e32 v186, v186
	v_mul_f32_e32 v187, v12, v228
	v_rndne_f32_e32 v187, v187
	v_cvt_i32_f32_e32 v187, v187
	v_mul_f32_e32 v188, v16, v228
	v_rndne_f32_e32 v188, v188
	v_cvt_i32_f32_e32 v188, v188
	v_mul_f32_e32 v189, v20, v228
	v_rndne_f32_e32 v189, v189
	v_cvt_i32_f32_e32 v189, v189
	v_and_b32_e32 v186, 0xff, v186
	v_and_b32_e32 v187, 0xff, v187
	v_and_b32_e32 v188, 0xff, v188
	v_lshl_or_b32 v190, v187, 8, v186
	v_lshl_or_b32 v190, v188, 16, v190
	v_lshl_or_b32 v190, v189, 24, v190
	ds_write_b32 v139, v190 offset:1024
	v_mul_f32_e32 v186, v9, v229
	v_rndne_f32_e32 v186, v186
	v_cvt_i32_f32_e32 v186, v186
	v_mul_f32_e32 v187, v13, v229
	v_rndne_f32_e32 v187, v187
	v_cvt_i32_f32_e32 v187, v187
	v_mul_f32_e32 v188, v17, v229
	v_rndne_f32_e32 v188, v188
	v_cvt_i32_f32_e32 v188, v188
	v_mul_f32_e32 v189, v21, v229
	v_rndne_f32_e32 v189, v189
	v_cvt_i32_f32_e32 v189, v189
	v_and_b32_e32 v186, 0xff, v186
	v_and_b32_e32 v187, 0xff, v187
	v_and_b32_e32 v188, 0xff, v188
	v_lshl_or_b32 v190, v187, 8, v186
	v_lshl_or_b32 v190, v188, 16, v190
	v_lshl_or_b32 v190, v189, 24, v190
	ds_write_b32 v139, v190 offset:1536
	s_cmp_ge_u32 s10, 0x200
	s_cbranch_scc1 .Lc16_gates_nopf_0
	global_load_dwordx4 v[6:9], v138, s[56:57]
	s_add_u32 s56, s56, 0x8000
	s_addc_u32 s57, s57, 0
	global_load_dwordx4 v[10:13], v138, s[56:57]
	s_add_u32 s56, s56, 0x8000
	s_addc_u32 s57, s57, 0
	global_load_dwordx4 v[14:17], v138, s[56:57]
	s_add_u32 s56, s56, 0x8000
	s_addc_u32 s57, s57, 0
	global_load_dwordx4 v[18:21], v138, s[56:57]
	s_add_u32 s56, s56, 0x1e8000
	s_addc_u32 s57, s57, 0
.Lc16_gates_nopf_0:
	v_mul_f32_e32 v186, v22, v226
	v_rndne_f32_e32 v186, v186
	v_cvt_i32_f32_e32 v186, v186
	v_mul_f32_e32 v187, v26, v226
	v_rndne_f32_e32 v187, v187
	v_cvt_i32_f32_e32 v187, v187
	v_mul_f32_e32 v188, v30, v226
	v_rndne_f32_e32 v188, v188
	v_cvt_i32_f32_e32 v188, v188
	v_mul_f32_e32 v189, v34, v226
	v_rndne_f32_e32 v189, v189
	v_cvt_i32_f32_e32 v189, v189
	v_and_b32_e32 v186, 0xff, v186
	v_and_b32_e32 v187, 0xff, v187
	v_and_b32_e32 v188, 0xff, v188
	v_lshl_or_b32 v190, v187, 8, v186
	v_lshl_or_b32 v190, v188, 16, v190
	v_lshl_or_b32 v190, v189, 24, v190
	ds_write_b32 v139, v190 offset:64
	v_mul_f32_e32 v186, v23, v227
	v_rndne_f32_e32 v186, v186
	v_cvt_i32_f32_e32 v186, v186
	v_mul_f32_e32 v187, v27, v227
	v_rndne_f32_e32 v187, v187
	v_cvt_i32_f32_e32 v187, v187
	v_mul_f32_e32 v188, v31, v227
	v_rndne_f32_e32 v188, v188
	v_cvt_i32_f32_e32 v188, v188
	v_mul_f32_e32 v189, v35, v227
	v_rndne_f32_e32 v189, v189
	v_cvt_i32_f32_e32 v189, v189
	v_and_b32_e32 v186, 0xff, v186
	v_and_b32_e32 v187, 0xff, v187
	v_and_b32_e32 v188, 0xff, v188
	v_lshl_or_b32 v190, v187, 8, v186
	v_lshl_or_b32 v190, v188, 16, v190
	v_lshl_or_b32 v190, v189, 24, v190
	ds_write_b32 v139, v190 offset:576
	v_mul_f32_e32 v186, v24, v228
	v_rndne_f32_e32 v186, v186
	v_cvt_i32_f32_e32 v186, v186
	v_mul_f32_e32 v187, v28, v228
	v_rndne_f32_e32 v187, v187
	v_cvt_i32_f32_e32 v187, v187
	v_mul_f32_e32 v188, v32, v228
	v_rndne_f32_e32 v188, v188
	v_cvt_i32_f32_e32 v188, v188
	v_mul_f32_e32 v189, v36, v228
	v_rndne_f32_e32 v189, v189
	v_cvt_i32_f32_e32 v189, v189
	v_and_b32_e32 v186, 0xff, v186
	v_and_b32_e32 v187, 0xff, v187
	v_and_b32_e32 v188, 0xff, v188
	v_lshl_or_b32 v190, v187, 8, v186
	v_lshl_or_b32 v190, v188, 16, v190
	v_lshl_or_b32 v190, v189, 24, v190
	ds_write_b32 v139, v190 offset:1088
	v_mul_f32_e32 v186, v25, v229
	v_rndne_f32_e32 v186, v186
	v_cvt_i32_f32_e32 v186, v186
	v_mul_f32_e32 v187, v29, v229
	v_rndne_f32_e32 v187, v187
	v_cvt_i32_f32_e32 v187, v187
	v_mul_f32_e32 v188, v33, v229
	v_rndne_f32_e32 v188, v188
	v_cvt_i32_f32_e32 v188, v188
	v_mul_f32_e32 v189, v37, v229
	v_rndne_f32_e32 v189, v189
	v_cvt_i32_f32_e32 v189, v189
	v_and_b32_e32 v186, 0xff, v186
	v_and_b32_e32 v187, 0xff, v187
	v_and_b32_e32 v188, 0xff, v188
	v_lshl_or_b32 v190, v187, 8, v186
	v_lshl_or_b32 v190, v188, 16, v190
	v_lshl_or_b32 v190, v189, 24, v190
	ds_write_b32 v139, v190 offset:1600
	s_cmp_ge_u32 s10, 0x200
	s_cbranch_scc1 .Lc16_gates_nopf_1
	global_load_dwordx4 v[22:25], v138, s[56:57]
	s_add_u32 s56, s56, 0x8000
	s_addc_u32 s57, s57, 0
	global_load_dwordx4 v[26:29], v138, s[56:57]
	s_add_u32 s56, s56, 0x8000
	s_addc_u32 s57, s57, 0
	global_load_dwordx4 v[30:33], v138, s[56:57]
	s_add_u32 s56, s56, 0x8000
	s_addc_u32 s57, s57, 0
	global_load_dwordx4 v[34:37], v138, s[56:57]
	s_add_u32 s56, s56, 0x1e8000
	s_addc_u32 s57, s57, 0
.Lc16_gates_nopf_1:
	v_mul_f32_e32 v186, v38, v226
	v_rndne_f32_e32 v186, v186
	v_cvt_i32_f32_e32 v186, v186
	v_mul_f32_e32 v187, v42, v226
	v_rndne_f32_e32 v187, v187
	v_cvt_i32_f32_e32 v187, v187
	v_mul_f32_e32 v188, v46, v226
	v_rndne_f32_e32 v188, v188
	v_cvt_i32_f32_e32 v188, v188
	v_mul_f32_e32 v189, v50, v226
	v_rndne_f32_e32 v189, v189
	v_cvt_i32_f32_e32 v189, v189
	v_and_b32_e32 v186, 0xff, v186
	v_and_b32_e32 v187, 0xff, v187
	v_and_b32_e32 v188, 0xff, v188
	v_lshl_or_b32 v190, v187, 8, v186
	v_lshl_or_b32 v190, v188, 16, v190
	v_lshl_or_b32 v190, v189, 24, v190
	ds_write_b32 v139, v190 offset:128
	v_mul_f32_e32 v186, v39, v227
	v_rndne_f32_e32 v186, v186
	v_cvt_i32_f32_e32 v186, v186
	v_mul_f32_e32 v187, v43, v227
	v_rndne_f32_e32 v187, v187
	v_cvt_i32_f32_e32 v187, v187
	v_mul_f32_e32 v188, v47, v227
	v_rndne_f32_e32 v188, v188
	v_cvt_i32_f32_e32 v188, v188
	v_mul_f32_e32 v189, v51, v227
	v_rndne_f32_e32 v189, v189
	v_cvt_i32_f32_e32 v189, v189
	v_and_b32_e32 v186, 0xff, v186
	v_and_b32_e32 v187, 0xff, v187
	v_and_b32_e32 v188, 0xff, v188
	v_lshl_or_b32 v190, v187, 8, v186
	v_lshl_or_b32 v190, v188, 16, v190
	v_lshl_or_b32 v190, v189, 24, v190
	ds_write_b32 v139, v190 offset:640
	v_mul_f32_e32 v186, v40, v228
	v_rndne_f32_e32 v186, v186
	v_cvt_i32_f32_e32 v186, v186
	v_mul_f32_e32 v187, v44, v228
	v_rndne_f32_e32 v187, v187
	v_cvt_i32_f32_e32 v187, v187
	v_mul_f32_e32 v188, v48, v228
	v_rndne_f32_e32 v188, v188
	v_cvt_i32_f32_e32 v188, v188
	v_mul_f32_e32 v189, v52, v228
	v_rndne_f32_e32 v189, v189
	v_cvt_i32_f32_e32 v189, v189
	v_and_b32_e32 v186, 0xff, v186
	v_and_b32_e32 v187, 0xff, v187
	v_and_b32_e32 v188, 0xff, v188
	v_lshl_or_b32 v190, v187, 8, v186
	v_lshl_or_b32 v190, v188, 16, v190
	v_lshl_or_b32 v190, v189, 24, v190
	ds_write_b32 v139, v190 offset:1152
	v_mul_f32_e32 v186, v41, v229
	v_rndne_f32_e32 v186, v186
	v_cvt_i32_f32_e32 v186, v186
	v_mul_f32_e32 v187, v45, v229
	v_rndne_f32_e32 v187, v187
	v_cvt_i32_f32_e32 v187, v187
	v_mul_f32_e32 v188, v49, v229
	v_rndne_f32_e32 v188, v188
	v_cvt_i32_f32_e32 v188, v188
	v_mul_f32_e32 v189, v53, v229
	v_rndne_f32_e32 v189, v189
	v_cvt_i32_f32_e32 v189, v189
	v_and_b32_e32 v186, 0xff, v186
	v_and_b32_e32 v187, 0xff, v187
	v_and_b32_e32 v188, 0xff, v188
	v_lshl_or_b32 v190, v187, 8, v186
	v_lshl_or_b32 v190, v188, 16, v190
	v_lshl_or_b32 v190, v189, 24, v190
	ds_write_b32 v139, v190 offset:1664
	s_cmp_ge_u32 s10, 0x200
	s_cbranch_scc1 .Lc16_gates_nopf_2
	global_load_dwordx4 v[38:41], v138, s[56:57]
	s_add_u32 s56, s56, 0x8000
	s_addc_u32 s57, s57, 0
	global_load_dwordx4 v[42:45], v138, s[56:57]
	s_add_u32 s56, s56, 0x8000
	s_addc_u32 s57, s57, 0
	global_load_dwordx4 v[46:49], v138, s[56:57]
	s_add_u32 s56, s56, 0x8000
	s_addc_u32 s57, s57, 0
	global_load_dwordx4 v[50:53], v138, s[56:57]
	s_add_u32 s56, s56, 0x1e8000
	s_addc_u32 s57, s57, 0
.Lc16_gates_nopf_2:
	v_mul_f32_e32 v186, v54, v226
	v_rndne_f32_e32 v186, v186
	v_cvt_i32_f32_e32 v186, v186
	v_mul_f32_e32 v187, v58, v226
	v_rndne_f32_e32 v187, v187
	v_cvt_i32_f32_e32 v187, v187
	v_mul_f32_e32 v188, v62, v226
	v_rndne_f32_e32 v188, v188
	v_cvt_i32_f32_e32 v188, v188
	v_mul_f32_e32 v189, v66, v226
	v_rndne_f32_e32 v189, v189
	v_cvt_i32_f32_e32 v189, v189
	v_and_b32_e32 v186, 0xff, v186
	v_and_b32_e32 v187, 0xff, v187
	v_and_b32_e32 v188, 0xff, v188
	v_lshl_or_b32 v190, v187, 8, v186
	v_lshl_or_b32 v190, v188, 16, v190
	v_lshl_or_b32 v190, v189, 24, v190
	ds_write_b32 v139, v190 offset:192
	v_mul_f32_e32 v186, v55, v227
	v_rndne_f32_e32 v186, v186
	v_cvt_i32_f32_e32 v186, v186
	v_mul_f32_e32 v187, v59, v227
	v_rndne_f32_e32 v187, v187
	v_cvt_i32_f32_e32 v187, v187
	v_mul_f32_e32 v188, v63, v227
	v_rndne_f32_e32 v188, v188
	v_cvt_i32_f32_e32 v188, v188
	v_mul_f32_e32 v189, v67, v227
	v_rndne_f32_e32 v189, v189
	v_cvt_i32_f32_e32 v189, v189
	v_and_b32_e32 v186, 0xff, v186
	v_and_b32_e32 v187, 0xff, v187
	v_and_b32_e32 v188, 0xff, v188
	v_lshl_or_b32 v190, v187, 8, v186
	v_lshl_or_b32 v190, v188, 16, v190
	v_lshl_or_b32 v190, v189, 24, v190
	ds_write_b32 v139, v190 offset:704
	v_mul_f32_e32 v186, v56, v228
	v_rndne_f32_e32 v186, v186
	v_cvt_i32_f32_e32 v186, v186
	v_mul_f32_e32 v187, v60, v228
	v_rndne_f32_e32 v187, v187
	v_cvt_i32_f32_e32 v187, v187
	v_mul_f32_e32 v188, v64, v228
	v_rndne_f32_e32 v188, v188
	v_cvt_i32_f32_e32 v188, v188
	v_mul_f32_e32 v189, v68, v228
	v_rndne_f32_e32 v189, v189
	v_cvt_i32_f32_e32 v189, v189
	v_and_b32_e32 v186, 0xff, v186
	v_and_b32_e32 v187, 0xff, v187
	v_and_b32_e32 v188, 0xff, v188
	v_lshl_or_b32 v190, v187, 8, v186
	v_lshl_or_b32 v190, v188, 16, v190
	v_lshl_or_b32 v190, v189, 24, v190
	ds_write_b32 v139, v190 offset:1216
	v_mul_f32_e32 v186, v57, v229
	v_rndne_f32_e32 v186, v186
	v_cvt_i32_f32_e32 v186, v186
	v_mul_f32_e32 v187, v61, v229
	v_rndne_f32_e32 v187, v187
	v_cvt_i32_f32_e32 v187, v187
	v_mul_f32_e32 v188, v65, v229
	v_rndne_f32_e32 v188, v188
	v_cvt_i32_f32_e32 v188, v188
	v_mul_f32_e32 v189, v69, v229
	v_rndne_f32_e32 v189, v189
	v_cvt_i32_f32_e32 v189, v189
	v_and_b32_e32 v186, 0xff, v186
	v_and_b32_e32 v187, 0xff, v187
	v_and_b32_e32 v188, 0xff, v188
	v_lshl_or_b32 v190, v187, 8, v186
	v_lshl_or_b32 v190, v188, 16, v190
	v_lshl_or_b32 v190, v189, 24, v190
	ds_write_b32 v139, v190 offset:1728
	s_cmp_ge_u32 s10, 0x200
	s_cbranch_scc1 .Lc16_gates_nopf_3
	global_load_dwordx4 v[54:57], v138, s[56:57]
	s_add_u32 s56, s56, 0x8000
	s_addc_u32 s57, s57, 0
	global_load_dwordx4 v[58:61], v138, s[56:57]
	s_add_u32 s56, s56, 0x8000
	s_addc_u32 s57, s57, 0
	global_load_dwordx4 v[62:65], v138, s[56:57]
	s_add_u32 s56, s56, 0x8000
	s_addc_u32 s57, s57, 0
	global_load_dwordx4 v[66:69], v138, s[56:57]
	s_add_u32 s56, s56, 0x1e8000
	s_addc_u32 s57, s57, 0
.Lc16_gates_nopf_3:
	v_mul_f32_e32 v186, v70, v226
	v_rndne_f32_e32 v186, v186
	v_cvt_i32_f32_e32 v186, v186
	v_mul_f32_e32 v187, v74, v226
	v_rndne_f32_e32 v187, v187
	v_cvt_i32_f32_e32 v187, v187
	v_mul_f32_e32 v188, v78, v226
	v_rndne_f32_e32 v188, v188
	v_cvt_i32_f32_e32 v188, v188
	v_mul_f32_e32 v189, v82, v226
	v_rndne_f32_e32 v189, v189
	v_cvt_i32_f32_e32 v189, v189
	v_and_b32_e32 v186, 0xff, v186
	v_and_b32_e32 v187, 0xff, v187
	v_and_b32_e32 v188, 0xff, v188
	v_lshl_or_b32 v190, v187, 8, v186
	v_lshl_or_b32 v190, v188, 16, v190
	v_lshl_or_b32 v190, v189, 24, v190
	ds_write_b32 v139, v190 offset:256
	v_mul_f32_e32 v186, v71, v227
	v_rndne_f32_e32 v186, v186
	v_cvt_i32_f32_e32 v186, v186
	v_mul_f32_e32 v187, v75, v227
	v_rndne_f32_e32 v187, v187
	v_cvt_i32_f32_e32 v187, v187
	v_mul_f32_e32 v188, v79, v227
	v_rndne_f32_e32 v188, v188
	v_cvt_i32_f32_e32 v188, v188
	v_mul_f32_e32 v189, v83, v227
	v_rndne_f32_e32 v189, v189
	v_cvt_i32_f32_e32 v189, v189
	v_and_b32_e32 v186, 0xff, v186
	v_and_b32_e32 v187, 0xff, v187
	v_and_b32_e32 v188, 0xff, v188
	v_lshl_or_b32 v190, v187, 8, v186
	v_lshl_or_b32 v190, v188, 16, v190
	v_lshl_or_b32 v190, v189, 24, v190
	ds_write_b32 v139, v190 offset:768
	v_mul_f32_e32 v186, v72, v228
	v_rndne_f32_e32 v186, v186
	v_cvt_i32_f32_e32 v186, v186
	v_mul_f32_e32 v187, v76, v228
	v_rndne_f32_e32 v187, v187
	v_cvt_i32_f32_e32 v187, v187
	v_mul_f32_e32 v188, v80, v228
	v_rndne_f32_e32 v188, v188
	v_cvt_i32_f32_e32 v188, v188
	v_mul_f32_e32 v189, v84, v228
	v_rndne_f32_e32 v189, v189
	v_cvt_i32_f32_e32 v189, v189
	v_and_b32_e32 v186, 0xff, v186
	v_and_b32_e32 v187, 0xff, v187
	v_and_b32_e32 v188, 0xff, v188
	v_lshl_or_b32 v190, v187, 8, v186
	v_lshl_or_b32 v190, v188, 16, v190
	v_lshl_or_b32 v190, v189, 24, v190
	ds_write_b32 v139, v190 offset:1280
	v_mul_f32_e32 v186, v73, v229
	v_rndne_f32_e32 v186, v186
	v_cvt_i32_f32_e32 v186, v186
	v_mul_f32_e32 v187, v77, v229
	v_rndne_f32_e32 v187, v187
	v_cvt_i32_f32_e32 v187, v187
	v_mul_f32_e32 v188, v81, v229
	v_rndne_f32_e32 v188, v188
	v_cvt_i32_f32_e32 v188, v188
	v_mul_f32_e32 v189, v85, v229
	v_rndne_f32_e32 v189, v189
	v_cvt_i32_f32_e32 v189, v189
	v_and_b32_e32 v186, 0xff, v186
	v_and_b32_e32 v187, 0xff, v187
	v_and_b32_e32 v188, 0xff, v188
	v_lshl_or_b32 v190, v187, 8, v186
	v_lshl_or_b32 v190, v188, 16, v190
	v_lshl_or_b32 v190, v189, 24, v190
	ds_write_b32 v139, v190 offset:1792
	s_cmp_ge_u32 s10, 0x200
	s_cbranch_scc1 .Lc16_gates_nopf_4
	global_load_dwordx4 v[70:73], v138, s[56:57]
	s_add_u32 s56, s56, 0x8000
	s_addc_u32 s57, s57, 0
	global_load_dwordx4 v[74:77], v138, s[56:57]
	s_add_u32 s56, s56, 0x8000
	s_addc_u32 s57, s57, 0
	global_load_dwordx4 v[78:81], v138, s[56:57]
	s_add_u32 s56, s56, 0x8000
	s_addc_u32 s57, s57, 0
	global_load_dwordx4 v[82:85], v138, s[56:57]
	s_add_u32 s56, s56, 0x1e8000
	s_addc_u32 s57, s57, 0
.Lc16_gates_nopf_4:
	v_mul_f32_e32 v186, v86, v226
	v_rndne_f32_e32 v186, v186
	v_cvt_i32_f32_e32 v186, v186
	v_mul_f32_e32 v187, v90, v226
	v_rndne_f32_e32 v187, v187
	v_cvt_i32_f32_e32 v187, v187
	v_mul_f32_e32 v188, v94, v226
	v_rndne_f32_e32 v188, v188
	v_cvt_i32_f32_e32 v188, v188
	v_mul_f32_e32 v189, v98, v226
	v_rndne_f32_e32 v189, v189
	v_cvt_i32_f32_e32 v189, v189
	v_and_b32_e32 v186, 0xff, v186
	v_and_b32_e32 v187, 0xff, v187
	v_and_b32_e32 v188, 0xff, v188
	v_lshl_or_b32 v190, v187, 8, v186
	v_lshl_or_b32 v190, v188, 16, v190
	v_lshl_or_b32 v190, v189, 24, v190
	ds_write_b32 v139, v190 offset:320
	v_mul_f32_e32 v186, v87, v227
	v_rndne_f32_e32 v186, v186
	v_cvt_i32_f32_e32 v186, v186
	v_mul_f32_e32 v187, v91, v227
	v_rndne_f32_e32 v187, v187
	v_cvt_i32_f32_e32 v187, v187
	v_mul_f32_e32 v188, v95, v227
	v_rndne_f32_e32 v188, v188
	v_cvt_i32_f32_e32 v188, v188
	v_mul_f32_e32 v189, v99, v227
	v_rndne_f32_e32 v189, v189
	v_cvt_i32_f32_e32 v189, v189
	v_and_b32_e32 v186, 0xff, v186
	v_and_b32_e32 v187, 0xff, v187
	v_and_b32_e32 v188, 0xff, v188
	v_lshl_or_b32 v190, v187, 8, v186
	v_lshl_or_b32 v190, v188, 16, v190
	v_lshl_or_b32 v190, v189, 24, v190
	ds_write_b32 v139, v190 offset:832
	v_mul_f32_e32 v186, v88, v228
	v_rndne_f32_e32 v186, v186
	v_cvt_i32_f32_e32 v186, v186
	v_mul_f32_e32 v187, v92, v228
	v_rndne_f32_e32 v187, v187
	v_cvt_i32_f32_e32 v187, v187
	v_mul_f32_e32 v188, v96, v228
	v_rndne_f32_e32 v188, v188
	v_cvt_i32_f32_e32 v188, v188
	v_mul_f32_e32 v189, v100, v228
	v_rndne_f32_e32 v189, v189
	v_cvt_i32_f32_e32 v189, v189
	v_and_b32_e32 v186, 0xff, v186
	v_and_b32_e32 v187, 0xff, v187
	v_and_b32_e32 v188, 0xff, v188
	v_lshl_or_b32 v190, v187, 8, v186
	v_lshl_or_b32 v190, v188, 16, v190
	v_lshl_or_b32 v190, v189, 24, v190
	ds_write_b32 v139, v190 offset:1344
	v_mul_f32_e32 v186, v89, v229
	v_rndne_f32_e32 v186, v186
	v_cvt_i32_f32_e32 v186, v186
	v_mul_f32_e32 v187, v93, v229
	v_rndne_f32_e32 v187, v187
	v_cvt_i32_f32_e32 v187, v187
	v_mul_f32_e32 v188, v97, v229
	v_rndne_f32_e32 v188, v188
	v_cvt_i32_f32_e32 v188, v188
	v_mul_f32_e32 v189, v101, v229
	v_rndne_f32_e32 v189, v189
	v_cvt_i32_f32_e32 v189, v189
	v_and_b32_e32 v186, 0xff, v186
	v_and_b32_e32 v187, 0xff, v187
	v_and_b32_e32 v188, 0xff, v188
	v_lshl_or_b32 v190, v187, 8, v186
	v_lshl_or_b32 v190, v188, 16, v190
	v_lshl_or_b32 v190, v189, 24, v190
	ds_write_b32 v139, v190 offset:1856
	s_cmp_ge_u32 s10, 0x200
	s_cbranch_scc1 .Lc16_gates_nopf_5
	global_load_dwordx4 v[86:89], v138, s[56:57]
	s_add_u32 s56, s56, 0x8000
	s_addc_u32 s57, s57, 0
	global_load_dwordx4 v[90:93], v138, s[56:57]
	s_add_u32 s56, s56, 0x8000
	s_addc_u32 s57, s57, 0
	global_load_dwordx4 v[94:97], v138, s[56:57]
	s_add_u32 s56, s56, 0x8000
	s_addc_u32 s57, s57, 0
	global_load_dwordx4 v[98:101], v138, s[56:57]
	s_add_u32 s56, s56, 0x1e8000
	s_addc_u32 s57, s57, 0
.Lc16_gates_nopf_5:
	v_mul_f32_e32 v186, v102, v226
	v_rndne_f32_e32 v186, v186
	v_cvt_i32_f32_e32 v186, v186
	v_mul_f32_e32 v187, v106, v226
	v_rndne_f32_e32 v187, v187
	v_cvt_i32_f32_e32 v187, v187
	v_mul_f32_e32 v188, v110, v226
	v_rndne_f32_e32 v188, v188
	v_cvt_i32_f32_e32 v188, v188
	v_mul_f32_e32 v189, v114, v226
	v_rndne_f32_e32 v189, v189
	v_cvt_i32_f32_e32 v189, v189
	v_and_b32_e32 v186, 0xff, v186
	v_and_b32_e32 v187, 0xff, v187
	v_and_b32_e32 v188, 0xff, v188
	v_lshl_or_b32 v190, v187, 8, v186
	v_lshl_or_b32 v190, v188, 16, v190
	v_lshl_or_b32 v190, v189, 24, v190
	ds_write_b32 v139, v190 offset:384
	v_mul_f32_e32 v186, v103, v227
	v_rndne_f32_e32 v186, v186
	v_cvt_i32_f32_e32 v186, v186
	v_mul_f32_e32 v187, v107, v227
	v_rndne_f32_e32 v187, v187
	v_cvt_i32_f32_e32 v187, v187
	v_mul_f32_e32 v188, v111, v227
	v_rndne_f32_e32 v188, v188
	v_cvt_i32_f32_e32 v188, v188
	v_mul_f32_e32 v189, v115, v227
	v_rndne_f32_e32 v189, v189
	v_cvt_i32_f32_e32 v189, v189
	v_and_b32_e32 v186, 0xff, v186
	v_and_b32_e32 v187, 0xff, v187
	v_and_b32_e32 v188, 0xff, v188
	v_lshl_or_b32 v190, v187, 8, v186
	v_lshl_or_b32 v190, v188, 16, v190
	v_lshl_or_b32 v190, v189, 24, v190
	ds_write_b32 v139, v190 offset:896
	v_mul_f32_e32 v186, v104, v228
	v_rndne_f32_e32 v186, v186
	v_cvt_i32_f32_e32 v186, v186
	v_mul_f32_e32 v187, v108, v228
	v_rndne_f32_e32 v187, v187
	v_cvt_i32_f32_e32 v187, v187
	v_mul_f32_e32 v188, v112, v228
	v_rndne_f32_e32 v188, v188
	v_cvt_i32_f32_e32 v188, v188
	v_mul_f32_e32 v189, v116, v228
	v_rndne_f32_e32 v189, v189
	v_cvt_i32_f32_e32 v189, v189
	v_and_b32_e32 v186, 0xff, v186
	v_and_b32_e32 v187, 0xff, v187
	v_and_b32_e32 v188, 0xff, v188
	v_lshl_or_b32 v190, v187, 8, v186
	v_lshl_or_b32 v190, v188, 16, v190
	v_lshl_or_b32 v190, v189, 24, v190
	ds_write_b32 v139, v190 offset:1408
	v_mul_f32_e32 v186, v105, v229
	v_rndne_f32_e32 v186, v186
	v_cvt_i32_f32_e32 v186, v186
	v_mul_f32_e32 v187, v109, v229
	v_rndne_f32_e32 v187, v187
	v_cvt_i32_f32_e32 v187, v187
	v_mul_f32_e32 v188, v113, v229
	v_rndne_f32_e32 v188, v188
	v_cvt_i32_f32_e32 v188, v188
	v_mul_f32_e32 v189, v117, v229
	v_rndne_f32_e32 v189, v189
	v_cvt_i32_f32_e32 v189, v189
	v_and_b32_e32 v186, 0xff, v186
	v_and_b32_e32 v187, 0xff, v187
	v_and_b32_e32 v188, 0xff, v188
	v_lshl_or_b32 v190, v187, 8, v186
	v_lshl_or_b32 v190, v188, 16, v190
	v_lshl_or_b32 v190, v189, 24, v190
	ds_write_b32 v139, v190 offset:1920
	s_cmp_ge_u32 s10, 0x200
	s_cbranch_scc1 .Lc16_gates_nopf_6
	global_load_dwordx4 v[102:105], v138, s[56:57]
	s_add_u32 s56, s56, 0x8000
	s_addc_u32 s57, s57, 0
	global_load_dwordx4 v[106:109], v138, s[56:57]
	s_add_u32 s56, s56, 0x8000
	s_addc_u32 s57, s57, 0
	global_load_dwordx4 v[110:113], v138, s[56:57]
	s_add_u32 s56, s56, 0x8000
	s_addc_u32 s57, s57, 0
	global_load_dwordx4 v[114:117], v138, s[56:57]
	s_add_u32 s56, s56, 0x1e8000
	s_addc_u32 s57, s57, 0
.Lc16_gates_nopf_6:
	v_mul_f32_e32 v186, v118, v226
	v_rndne_f32_e32 v186, v186
	v_cvt_i32_f32_e32 v186, v186
	v_mul_f32_e32 v187, v122, v226
	v_rndne_f32_e32 v187, v187
	v_cvt_i32_f32_e32 v187, v187
	v_mul_f32_e32 v188, v126, v226
	v_rndne_f32_e32 v188, v188
	v_cvt_i32_f32_e32 v188, v188
	v_mul_f32_e32 v189, v130, v226
	v_rndne_f32_e32 v189, v189
	v_cvt_i32_f32_e32 v189, v189
	v_and_b32_e32 v186, 0xff, v186
	v_and_b32_e32 v187, 0xff, v187
	v_and_b32_e32 v188, 0xff, v188
	v_lshl_or_b32 v190, v187, 8, v186
	v_lshl_or_b32 v190, v188, 16, v190
	v_lshl_or_b32 v190, v189, 24, v190
	ds_write_b32 v139, v190 offset:448
	v_mul_f32_e32 v186, v119, v227
	v_rndne_f32_e32 v186, v186
	v_cvt_i32_f32_e32 v186, v186
	v_mul_f32_e32 v187, v123, v227
	v_rndne_f32_e32 v187, v187
	v_cvt_i32_f32_e32 v187, v187
	v_mul_f32_e32 v188, v127, v227
	v_rndne_f32_e32 v188, v188
	v_cvt_i32_f32_e32 v188, v188
	v_mul_f32_e32 v189, v131, v227
	v_rndne_f32_e32 v189, v189
	v_cvt_i32_f32_e32 v189, v189
	v_and_b32_e32 v186, 0xff, v186
	v_and_b32_e32 v187, 0xff, v187
	v_and_b32_e32 v188, 0xff, v188
	v_lshl_or_b32 v190, v187, 8, v186
	v_lshl_or_b32 v190, v188, 16, v190
	v_lshl_or_b32 v190, v189, 24, v190
	ds_write_b32 v139, v190 offset:960
	v_mul_f32_e32 v186, v120, v228
	v_rndne_f32_e32 v186, v186
	v_cvt_i32_f32_e32 v186, v186
	v_mul_f32_e32 v187, v124, v228
	v_rndne_f32_e32 v187, v187
	v_cvt_i32_f32_e32 v187, v187
	v_mul_f32_e32 v188, v128, v228
	v_rndne_f32_e32 v188, v188
	v_cvt_i32_f32_e32 v188, v188
	v_mul_f32_e32 v189, v132, v228
	v_rndne_f32_e32 v189, v189
	v_cvt_i32_f32_e32 v189, v189
	v_and_b32_e32 v186, 0xff, v186
	v_and_b32_e32 v187, 0xff, v187
	v_and_b32_e32 v188, 0xff, v188
	v_lshl_or_b32 v190, v187, 8, v186
	v_lshl_or_b32 v190, v188, 16, v190
	v_lshl_or_b32 v190, v189, 24, v190
	ds_write_b32 v139, v190 offset:1472
	v_mul_f32_e32 v186, v121, v229
	v_rndne_f32_e32 v186, v186
	v_cvt_i32_f32_e32 v186, v186
	v_mul_f32_e32 v187, v125, v229
	v_rndne_f32_e32 v187, v187
	v_cvt_i32_f32_e32 v187, v187
	v_mul_f32_e32 v188, v129, v229
	v_rndne_f32_e32 v188, v188
	v_cvt_i32_f32_e32 v188, v188
	v_mul_f32_e32 v189, v133, v229
	v_rndne_f32_e32 v189, v189
	v_cvt_i32_f32_e32 v189, v189
	v_and_b32_e32 v186, 0xff, v186
	v_and_b32_e32 v187, 0xff, v187
	v_and_b32_e32 v188, 0xff, v188
	v_lshl_or_b32 v190, v187, 8, v186
	v_lshl_or_b32 v190, v188, 16, v190
	v_lshl_or_b32 v190, v189, 24, v190
	ds_write_b32 v139, v190 offset:1984
	s_cmp_ge_u32 s10, 0x200
	s_cbranch_scc1 .Lc16_gates_nopf_7
	global_load_dwordx4 v[118:121], v138, s[56:57]
	s_add_u32 s56, s56, 0x8000
	s_addc_u32 s57, s57, 0
	global_load_dwordx4 v[122:125], v138, s[56:57]
	s_add_u32 s56, s56, 0x8000
	s_addc_u32 s57, s57, 0
	global_load_dwordx4 v[126:129], v138, s[56:57]
	s_add_u32 s56, s56, 0x8000
	s_addc_u32 s57, s57, 0
	global_load_dwordx4 v[130:133], v138, s[56:57]

.Lc16_gates_done:
	v_readlane_b32 s48, v255, 19
	v_readlane_b32 s49, v255, 20
	v_mul_u32_u24_e32 v138, 0x56000, v136
	v_lshl_add_u32 v138, v137, 4, v138
	s_mul_i32 s3, s1, 0x2b00000
	s_nop 1
	s_add_u32 s48, s48, s3
	s_addc_u32 s49, s49, 0
	s_mov_b32 s0, s72
	s_cmp_ge_u32 s0, 0x560
	s_cbranch_scc1 .Lc16_ffn1_done
	s_lshl_b32 s3, s0, 6
	s_add_u32 s56, s48, s3
	s_addc_u32 s57, s49, 0
	global_load_dwordx4 v[6:9], v138, s[56:57]
	s_add_u32 s56, s56, 0x15800
	s_addc_u32 s57, s57, 0
	global_load_dwordx4 v[10:13], v138, s[56:57]
	s_add_u32 s56, s56, 0x15800
	s_addc_u32 s57, s57, 0
	global_load_dwordx4 v[14:17], v138, s[56:57]
	s_add_u32 s56, s56, 0x15800
	s_addc_u32 s57, s57, 0
	global_load_dwordx4 v[18:21], v138, s[56:57]
	s_add_u32 s56, s56, 0x51f800
	s_addc_u32 s57, s57, 0
	global_load_dwordx4 v[22:25], v138, s[56:57]
	s_add_u32 s56, s56, 0x15800
	s_addc_u32 s57, s57, 0
	global_load_dwordx4 v[26:29], v138, s[56:57]
	s_add_u32 s56, s56, 0x15800
	s_addc_u32 s57, s57, 0
	global_load_dwordx4 v[30:33], v138, s[56:57]
	s_add_u32 s56, s56, 0x15800
	s_addc_u32 s57, s57, 0
	global_load_dwordx4 v[34:37], v138, s[56:57]
	s_add_u32 s56, s56, 0x51f800
	s_addc_u32 s57, s57, 0
	global_load_dwordx4 v[38:41], v138, s[56:57]
	s_add_u32 s56, s56, 0x15800
	s_addc_u32 s57, s57, 0
	global_load_dwordx4 v[42:45], v138, s[56:57]
	s_add_u32 s56, s56, 0x15800
	s_addc_u32 s57, s57, 0
	global_load_dwordx4 v[46:49], v138, s[56:57]
	s_add_u32 s56, s56, 0x15800
	s_addc_u32 s57, s57, 0
	global_load_dwordx4 v[50:53], v138, s[56:57]
	s_add_u32 s56, s56, 0x51f800
	s_addc_u32 s57, s57, 0
	global_load_dwordx4 v[54:57], v138, s[56:57]
	s_add_u32 s56, s56, 0x15800
	s_addc_u32 s57, s57, 0
	global_load_dwordx4 v[58:61], v138, s[56:57]
	s_add_u32 s56, s56, 0x15800
	s_addc_u32 s57, s57, 0
	global_load_dwordx4 v[62:65], v138, s[56:57]
	s_add_u32 s56, s56, 0x15800
	s_addc_u32 s57, s57, 0
	global_load_dwordx4 v[66:69], v138, s[56:57]
	s_add_u32 s56, s56, 0x51f800
	s_addc_u32 s57, s57, 0
	global_load_dwordx4 v[70:73], v138, s[56:57]
	s_add_u32 s56, s56, 0x15800
	s_addc_u32 s57, s57, 0
	global_load_dwordx4 v[74:77], v138, s[56:57]
	s_add_u32 s56, s56, 0x15800
	s_addc_u32 s57, s57, 0
	global_load_dwordx4 v[78:81], v138, s[56:57]
	s_add_u32 s56, s56, 0x15800
	s_addc_u32 s57, s57, 0
	global_load_dwordx4 v[82:85], v138, s[56:57]
	s_add_u32 s56, s56, 0x51f800
	s_addc_u32 s57, s57, 0
	global_load_dwordx4 v[86:89], v138, s[56:57]
	s_add_u32 s56, s56, 0x15800
	s_addc_u32 s57, s57, 0
	global_load_dwordx4 v[90:93], v138, s[56:57]
	s_add_u32 s56, s56, 0x15800
	s_addc_u32 s57, s57, 0
	global_load_dwordx4 v[94:97], v138, s[56:57]
	s_add_u32 s56, s56, 0x15800
	s_addc_u32 s57, s57, 0
	global_load_dwordx4 v[98:101], v138, s[56:57]
	s_add_u32 s56, s56, 0x51f800
	s_addc_u32 s57, s57, 0
	global_load_dwordx4 v[102:105], v138, s[56:57]
	s_add_u32 s56, s56, 0x15800
	s_addc_u32 s57, s57, 0
	global_load_dwordx4 v[106:109], v138, s[56:57]
	s_add_u32 s56, s56, 0x15800
	s_addc_u32 s57, s57, 0
	global_load_dwordx4 v[110:113], v138, s[56:57]
	s_add_u32 s56, s56, 0x15800
	s_addc_u32 s57, s57, 0
	global_load_dwordx4 v[114:117], v138, s[56:57]
	s_add_u32 s56, s56, 0x51f800
	s_addc_u32 s57, s57, 0
	global_load_dwordx4 v[118:121], v138, s[56:57]
	s_add_u32 s56, s56, 0x15800
	s_addc_u32 s57, s57, 0
	global_load_dwordx4 v[122:125], v138, s[56:57]
	s_add_u32 s56, s56, 0x15800
	s_addc_u32 s57, s57, 0
	global_load_dwordx4 v[126:129], v138, s[56:57]
	s_add_u32 s56, s56, 0x15800
	s_addc_u32 s57, s57, 0
	global_load_dwordx4 v[130:133], v138, s[56:57]

.Lc16_ffn1_nocm:
	v_div_scale_f32 v175, s[70:71], v220, v220, s74
	v_rcp_f32_e32 v176, v175
	s_nop 0
	v_fma_f32 v177, -v175, v176, 1.0
	v_fmac_f32_e32 v176, v177, v176
	v_div_scale_f32 v177, vcc, s74, v220, s74
	v_mul_f32_e32 v178, v177, v176
	v_fma_f32 v180, -v175, v178, v177
	v_fmac_f32_e32 v178, v180, v176
	v_fma_f32 v175, -v175, v178, v177
	s_nop 0
	v_div_fmas_f32 v175, v175, v176, v178
	v_div_fixup_f32 v175, v175, v220, s74
	v_cmp_lt_f32_e32 vcc, 0, v220
	s_nop 1
	v_cndmask_b32_e32 v226, 0, v175, vcc
	v_div_scale_f32 v175, s[70:71], v221, v221, s74
	v_rcp_f32_e32 v176, v175
	s_nop 0
	v_fma_f32 v177, -v175, v176, 1.0
	v_fmac_f32_e32 v176, v177, v176
	v_div_scale_f32 v177, vcc, s74, v221, s74
	v_mul_f32_e32 v178, v177, v176
	v_fma_f32 v180, -v175, v178, v177
	v_fmac_f32_e32 v178, v180, v176
	v_fma_f32 v175, -v175, v178, v177
	s_nop 0
	v_div_fmas_f32 v175, v175, v176, v178
	v_div_fixup_f32 v175, v175, v221, s74
	v_cmp_lt_f32_e32 vcc, 0, v221
	s_nop 1
	v_cndmask_b32_e32 v227, 0, v175, vcc
	v_div_scale_f32 v175, s[70:71], v222, v222, s74
	v_rcp_f32_e32 v176, v175
	s_nop 0
	v_fma_f32 v177, -v175, v176, 1.0
	v_fmac_f32_e32 v176, v177, v176
	v_div_scale_f32 v177, vcc, s74, v222, s74
	v_mul_f32_e32 v178, v177, v176
	v_fma_f32 v180, -v175, v178, v177
	v_fmac_f32_e32 v178, v180, v176
	v_fma_f32 v175, -v175, v178, v177
	s_nop 0
	v_div_fmas_f32 v175, v175, v176, v178
	v_div_fixup_f32 v175, v175, v222, s74
	v_cmp_lt_f32_e32 vcc, 0, v222
	s_nop 1
	v_cndmask_b32_e32 v228, 0, v175, vcc
	v_div_scale_f32 v175, s[70:71], v223, v223, s74
	v_rcp_f32_e32 v176, v175
	s_nop 0
	v_fma_f32 v177, -v175, v176, 1.0
	v_fmac_f32_e32 v176, v177, v176
	v_div_scale_f32 v177, vcc, s74, v223, s74
	v_mul_f32_e32 v178, v177, v176
	v_fma_f32 v180, -v175, v178, v177
	v_fmac_f32_e32 v178, v180, v176
	v_fma_f32 v175, -v175, v178, v177
	s_nop 0
	v_div_fmas_f32 v175, v175, v176, v178
	v_div_fixup_f32 v175, v175, v223, s74
	v_cmp_lt_f32_e32 vcc, 0, v223
	s_nop 1
	v_cndmask_b32_e32 v229, 0, v175, vcc
	s_add_u32 s10, s0, s33
	s_lshl_b32 s3, s10, 6
	s_add_u32 s56, s48, s3
	s_addc_u32 s57, s49, 0
	v_mul_f32_e32 v186, v6, v226
	v_rndne_f32_e32 v186, v186
	v_cvt_i32_f32_e32 v186, v186
	v_mul_f32_e32 v187, v10, v226
	v_rndne_f32_e32 v187, v187
	v_cvt_i32_f32_e32 v187, v187
	v_mul_f32_e32 v188, v14, v226
	v_rndne_f32_e32 v188, v188
	v_cvt_i32_f32_e32 v188, v188
	v_mul_f32_e32 v189, v18, v226
	v_rndne_f32_e32 v189, v189
	v_cvt_i32_f32_e32 v189, v189
	v_and_b32_e32 v186, 0xff, v186
	v_and_b32_e32 v187, 0xff, v187
	v_and_b32_e32 v188, 0xff, v188
	v_lshl_or_b32 v190, v187, 8, v186
	v_lshl_or_b32 v190, v188, 16, v190
	v_lshl_or_b32 v190, v189, 24, v190
	ds_write_b32 v139, v190 offset:0
	v_mul_f32_e32 v186, v7, v227
	v_rndne_f32_e32 v186, v186
	v_cvt_i32_f32_e32 v186, v186
	v_mul_f32_e32 v187, v11, v227
	v_rndne_f32_e32 v187, v187
	v_cvt_i32_f32_e32 v187, v187
	v_mul_f32_e32 v188, v15, v227
	v_rndne_f32_e32 v188, v188
	v_cvt_i32_f32_e32 v188, v188
	v_mul_f32_e32 v189, v19, v227
	v_rndne_f32_e32 v189, v189
	v_cvt_i32_f32_e32 v189, v189
	v_and_b32_e32 v186, 0xff, v186
	v_and_b32_e32 v187, 0xff, v187
	v_and_b32_e32 v188, 0xff, v188
	v_lshl_or_b32 v190, v187, 8, v186
	v_lshl_or_b32 v190, v188, 16, v190
	v_lshl_or_b32 v190, v189, 24, v190
	ds_write_b32 v139, v190 offset:512
	v_mul_f32_e32 v186, v8, v228
	v_rndne_f32_e32 v186, v186
	v_cvt_i32_f32_e32 v186, v186
	v_mul_f32_e32 v187, v12, v228
	v_rndne_f32_e32 v187, v187
	v_cvt_i32_f32_e32 v187, v187
	v_mul_f32_e32 v188, v16, v228
	v_rndne_f32_e32 v188, v188
	v_cvt_i32_f32_e32 v188, v188
	v_mul_f32_e32 v189, v20, v228
	v_rndne_f32_e32 v189, v189
	v_cvt_i32_f32_e32 v189, v189
	v_and_b32_e32 v186, 0xff, v186
	v_and_b32_e32 v187, 0xff, v187
	v_and_b32_e32 v188, 0xff, v188
	v_lshl_or_b32 v190, v187, 8, v186
	v_lshl_or_b32 v190, v188, 16, v190
	v_lshl_or_b32 v190, v189, 24, v190
	ds_write_b32 v139, v190 offset:1024
	v_mul_f32_e32 v186, v9, v229
	v_rndne_f32_e32 v186, v186
	v_cvt_i32_f32_e32 v186, v186
	v_mul_f32_e32 v187, v13, v229
	v_rndne_f32_e32 v187, v187
	v_cvt_i32_f32_e32 v187, v187
	v_mul_f32_e32 v188, v17, v229
	v_rndne_f32_e32 v188, v188
	v_cvt_i32_f32_e32 v188, v188
	v_mul_f32_e32 v189, v21, v229
	v_rndne_f32_e32 v189, v189
	v_cvt_i32_f32_e32 v189, v189
	v_and_b32_e32 v186, 0xff, v186
	v_and_b32_e32 v187, 0xff, v187
	v_and_b32_e32 v188, 0xff, v188
	v_lshl_or_b32 v190, v187, 8, v186
	v_lshl_or_b32 v190, v188, 16, v190
	v_lshl_or_b32 v190, v189, 24, v190
	ds_write_b32 v139, v190 offset:1536
	s_cmp_ge_u32 s10, 0x560
	s_cbranch_scc1 .Lc16_ffn1_nopf_0
	global_load_dwordx4 v[6:9], v138, s[56:57]
	s_add_u32 s56, s56, 0x15800
	s_addc_u32 s57, s57, 0
	global_load_dwordx4 v[10:13], v138, s[56:57]
	s_add_u32 s56, s56, 0x15800
	s_addc_u32 s57, s57, 0
	global_load_dwordx4 v[14:17], v138, s[56:57]
	s_add_u32 s56, s56, 0x15800
	s_addc_u32 s57, s57, 0
	global_load_dwordx4 v[18:21], v138, s[56:57]
	s_add_u32 s56, s56, 0x51f800
	s_addc_u32 s57, s57, 0
.Lc16_ffn1_nopf_0:
	v_mul_f32_e32 v186, v22, v226
	v_rndne_f32_e32 v186, v186
	v_cvt_i32_f32_e32 v186, v186
	v_mul_f32_e32 v187, v26, v226
	v_rndne_f32_e32 v187, v187
	v_cvt_i32_f32_e32 v187, v187
	v_mul_f32_e32 v188, v30, v226
	v_rndne_f32_e32 v188, v188
	v_cvt_i32_f32_e32 v188, v188
	v_mul_f32_e32 v189, v34, v226
	v_rndne_f32_e32 v189, v189
	v_cvt_i32_f32_e32 v189, v189
	v_and_b32_e32 v186, 0xff, v186
	v_and_b32_e32 v187, 0xff, v187
	v_and_b32_e32 v188, 0xff, v188
	v_lshl_or_b32 v190, v187, 8, v186
	v_lshl_or_b32 v190, v188, 16, v190
	v_lshl_or_b32 v190, v189, 24, v190
	ds_write_b32 v139, v190 offset:64
	v_mul_f32_e32 v186, v23, v227
	v_rndne_f32_e32 v186, v186
	v_cvt_i32_f32_e32 v186, v186
	v_mul_f32_e32 v187, v27, v227
	v_rndne_f32_e32 v187, v187
	v_cvt_i32_f32_e32 v187, v187
	v_mul_f32_e32 v188, v31, v227
	v_rndne_f32_e32 v188, v188
	v_cvt_i32_f32_e32 v188, v188
	v_mul_f32_e32 v189, v35, v227
	v_rndne_f32_e32 v189, v189
	v_cvt_i32_f32_e32 v189, v189
	v_and_b32_e32 v186, 0xff, v186
	v_and_b32_e32 v187, 0xff, v187
	v_and_b32_e32 v188, 0xff, v188
	v_lshl_or_b32 v190, v187, 8, v186
	v_lshl_or_b32 v190, v188, 16, v190
	v_lshl_or_b32 v190, v189, 24, v190
	ds_write_b32 v139, v190 offset:576
	v_mul_f32_e32 v186, v24, v228
	v_rndne_f32_e32 v186, v186
	v_cvt_i32_f32_e32 v186, v186
	v_mul_f32_e32 v187, v28, v228
	v_rndne_f32_e32 v187, v187
	v_cvt_i32_f32_e32 v187, v187
	v_mul_f32_e32 v188, v32, v228
	v_rndne_f32_e32 v188, v188
	v_cvt_i32_f32_e32 v188, v188
	v_mul_f32_e32 v189, v36, v228
	v_rndne_f32_e32 v189, v189
	v_cvt_i32_f32_e32 v189, v189
	v_and_b32_e32 v186, 0xff, v186
	v_and_b32_e32 v187, 0xff, v187
	v_and_b32_e32 v188, 0xff, v188
	v_lshl_or_b32 v190, v187, 8, v186
	v_lshl_or_b32 v190, v188, 16, v190
	v_lshl_or_b32 v190, v189, 24, v190
	ds_write_b32 v139, v190 offset:1088
	v_mul_f32_e32 v186, v25, v229
	v_rndne_f32_e32 v186, v186
	v_cvt_i32_f32_e32 v186, v186
	v_mul_f32_e32 v187, v29, v229
	v_rndne_f32_e32 v187, v187
	v_cvt_i32_f32_e32 v187, v187
	v_mul_f32_e32 v188, v33, v229
	v_rndne_f32_e32 v188, v188
	v_cvt_i32_f32_e32 v188, v188
	v_mul_f32_e32 v189, v37, v229
	v_rndne_f32_e32 v189, v189
	v_cvt_i32_f32_e32 v189, v189
	v_and_b32_e32 v186, 0xff, v186
	v_and_b32_e32 v187, 0xff, v187
	v_and_b32_e32 v188, 0xff, v188
	v_lshl_or_b32 v190, v187, 8, v186
	v_lshl_or_b32 v190, v188, 16, v190
	v_lshl_or_b32 v190, v189, 24, v190
	ds_write_b32 v139, v190 offset:1600
	s_cmp_ge_u32 s10, 0x560
	s_cbranch_scc1 .Lc16_ffn1_nopf_1
	global_load_dwordx4 v[22:25], v138, s[56:57]
	s_add_u32 s56, s56, 0x15800
	s_addc_u32 s57, s57, 0
	global_load_dwordx4 v[26:29], v138, s[56:57]
	s_add_u32 s56, s56, 0x15800
	s_addc_u32 s57, s57, 0
	global_load_dwordx4 v[30:33], v138, s[56:57]
	s_add_u32 s56, s56, 0x15800
	s_addc_u32 s57, s57, 0
	global_load_dwordx4 v[34:37], v138, s[56:57]
	s_add_u32 s56, s56, 0x51f800
	s_addc_u32 s57, s57, 0
.Lc16_ffn1_nopf_1:
	v_mul_f32_e32 v186, v38, v226
	v_rndne_f32_e32 v186, v186
	v_cvt_i32_f32_e32 v186, v186
	v_mul_f32_e32 v187, v42, v226
	v_rndne_f32_e32 v187, v187
	v_cvt_i32_f32_e32 v187, v187
	v_mul_f32_e32 v188, v46, v226
	v_rndne_f32_e32 v188, v188
	v_cvt_i32_f32_e32 v188, v188
	v_mul_f32_e32 v189, v50, v226
	v_rndne_f32_e32 v189, v189
	v_cvt_i32_f32_e32 v189, v189
	v_and_b32_e32 v186, 0xff, v186
	v_and_b32_e32 v187, 0xff, v187
	v_and_b32_e32 v188, 0xff, v188
	v_lshl_or_b32 v190, v187, 8, v186
	v_lshl_or_b32 v190, v188, 16, v190
	v_lshl_or_b32 v190, v189, 24, v190
	ds_write_b32 v139, v190 offset:128
	v_mul_f32_e32 v186, v39, v227
	v_rndne_f32_e32 v186, v186
	v_cvt_i32_f32_e32 v186, v186
	v_mul_f32_e32 v187, v43, v227
	v_rndne_f32_e32 v187, v187
	v_cvt_i32_f32_e32 v187, v187
	v_mul_f32_e32 v188, v47, v227
	v_rndne_f32_e32 v188, v188
	v_cvt_i32_f32_e32 v188, v188
	v_mul_f32_e32 v189, v51, v227
	v_rndne_f32_e32 v189, v189
	v_cvt_i32_f32_e32 v189, v189
	v_and_b32_e32 v186, 0xff, v186
	v_and_b32_e32 v187, 0xff, v187
	v_and_b32_e32 v188, 0xff, v188
	v_lshl_or_b32 v190, v187, 8, v186
	v_lshl_or_b32 v190, v188, 16, v190
	v_lshl_or_b32 v190, v189, 24, v190
	ds_write_b32 v139, v190 offset:640
	v_mul_f32_e32 v186, v40, v228
	v_rndne_f32_e32 v186, v186
	v_cvt_i32_f32_e32 v186, v186
	v_mul_f32_e32 v187, v44, v228
	v_rndne_f32_e32 v187, v187
	v_cvt_i32_f32_e32 v187, v187
	v_mul_f32_e32 v188, v48, v228
	v_rndne_f32_e32 v188, v188
	v_cvt_i32_f32_e32 v188, v188
	v_mul_f32_e32 v189, v52, v228
	v_rndne_f32_e32 v189, v189
	v_cvt_i32_f32_e32 v189, v189
	v_and_b32_e32 v186, 0xff, v186
	v_and_b32_e32 v187, 0xff, v187
	v_and_b32_e32 v188, 0xff, v188
	v_lshl_or_b32 v190, v187, 8, v186
	v_lshl_or_b32 v190, v188, 16, v190
	v_lshl_or_b32 v190, v189, 24, v190
	ds_write_b32 v139, v190 offset:1152
	v_mul_f32_e32 v186, v41, v229
	v_rndne_f32_e32 v186, v186
	v_cvt_i32_f32_e32 v186, v186
	v_mul_f32_e32 v187, v45, v229
	v_rndne_f32_e32 v187, v187
	v_cvt_i32_f32_e32 v187, v187
	v_mul_f32_e32 v188, v49, v229
	v_rndne_f32_e32 v188, v188
	v_cvt_i32_f32_e32 v188, v188
	v_mul_f32_e32 v189, v53, v229
	v_rndne_f32_e32 v189, v189
	v_cvt_i32_f32_e32 v189, v189
	v_and_b32_e32 v186, 0xff, v186
	v_and_b32_e32 v187, 0xff, v187
	v_and_b32_e32 v188, 0xff, v188
	v_lshl_or_b32 v190, v187, 8, v186
	v_lshl_or_b32 v190, v188, 16, v190
	v_lshl_or_b32 v190, v189, 24, v190
	ds_write_b32 v139, v190 offset:1664
	s_cmp_ge_u32 s10, 0x560
	s_cbranch_scc1 .Lc16_ffn1_nopf_2
	global_load_dwordx4 v[38:41], v138, s[56:57]
	s_add_u32 s56, s56, 0x15800
	s_addc_u32 s57, s57, 0
	global_load_dwordx4 v[42:45], v138, s[56:57]
	s_add_u32 s56, s56, 0x15800
	s_addc_u32 s57, s57, 0
	global_load_dwordx4 v[46:49], v138, s[56:57]
	s_add_u32 s56, s56, 0x15800
	s_addc_u32 s57, s57, 0
	global_load_dwordx4 v[50:53], v138, s[56:57]
	s_add_u32 s56, s56, 0x51f800
	s_addc_u32 s57, s57, 0
.Lc16_ffn1_nopf_2:
	v_mul_f32_e32 v186, v54, v226
	v_rndne_f32_e32 v186, v186
	v_cvt_i32_f32_e32 v186, v186
	v_mul_f32_e32 v187, v58, v226
	v_rndne_f32_e32 v187, v187
	v_cvt_i32_f32_e32 v187, v187
	v_mul_f32_e32 v188, v62, v226
	v_rndne_f32_e32 v188, v188
	v_cvt_i32_f32_e32 v188, v188
	v_mul_f32_e32 v189, v66, v226
	v_rndne_f32_e32 v189, v189
	v_cvt_i32_f32_e32 v189, v189
	v_and_b32_e32 v186, 0xff, v186
	v_and_b32_e32 v187, 0xff, v187
	v_and_b32_e32 v188, 0xff, v188
	v_lshl_or_b32 v190, v187, 8, v186
	v_lshl_or_b32 v190, v188, 16, v190
	v_lshl_or_b32 v190, v189, 24, v190
	ds_write_b32 v139, v190 offset:192
	v_mul_f32_e32 v186, v55, v227
	v_rndne_f32_e32 v186, v186
	v_cvt_i32_f32_e32 v186, v186
	v_mul_f32_e32 v187, v59, v227
	v_rndne_f32_e32 v187, v187
	v_cvt_i32_f32_e32 v187, v187
	v_mul_f32_e32 v188, v63, v227
	v_rndne_f32_e32 v188, v188
	v_cvt_i32_f32_e32 v188, v188
	v_mul_f32_e32 v189, v67, v227
	v_rndne_f32_e32 v189, v189
	v_cvt_i32_f32_e32 v189, v189
	v_and_b32_e32 v186, 0xff, v186
	v_and_b32_e32 v187, 0xff, v187
	v_and_b32_e32 v188, 0xff, v188
	v_lshl_or_b32 v190, v187, 8, v186
	v_lshl_or_b32 v190, v188, 16, v190
	v_lshl_or_b32 v190, v189, 24, v190
	ds_write_b32 v139, v190 offset:704
	v_mul_f32_e32 v186, v56, v228
	v_rndne_f32_e32 v186, v186
	v_cvt_i32_f32_e32 v186, v186
	v_mul_f32_e32 v187, v60, v228
	v_rndne_f32_e32 v187, v187
	v_cvt_i32_f32_e32 v187, v187
	v_mul_f32_e32 v188, v64, v228
	v_rndne_f32_e32 v188, v188
	v_cvt_i32_f32_e32 v188, v188
	v_mul_f32_e32 v189, v68, v228
	v_rndne_f32_e32 v189, v189
	v_cvt_i32_f32_e32 v189, v189
	v_and_b32_e32 v186, 0xff, v186
	v_and_b32_e32 v187, 0xff, v187
	v_and_b32_e32 v188, 0xff, v188
	v_lshl_or_b32 v190, v187, 8, v186
	v_lshl_or_b32 v190, v188, 16, v190
	v_lshl_or_b32 v190, v189, 24, v190
	ds_write_b32 v139, v190 offset:1216
	v_mul_f32_e32 v186, v57, v229
	v_rndne_f32_e32 v186, v186
	v_cvt_i32_f32_e32 v186, v186
	v_mul_f32_e32 v187, v61, v229
	v_rndne_f32_e32 v187, v187
	v_cvt_i32_f32_e32 v187, v187
	v_mul_f32_e32 v188, v65, v229
	v_rndne_f32_e32 v188, v188
	v_cvt_i32_f32_e32 v188, v188
	v_mul_f32_e32 v189, v69, v229
	v_rndne_f32_e32 v189, v189
	v_cvt_i32_f32_e32 v189, v189
	v_and_b32_e32 v186, 0xff, v186
	v_and_b32_e32 v187, 0xff, v187
	v_and_b32_e32 v188, 0xff, v188
	v_lshl_or_b32 v190, v187, 8, v186
	v_lshl_or_b32 v190, v188, 16, v190
	v_lshl_or_b32 v190, v189, 24, v190
	ds_write_b32 v139, v190 offset:1728
	s_cmp_ge_u32 s10, 0x560
	s_cbranch_scc1 .Lc16_ffn1_nopf_3
	global_load_dwordx4 v[54:57], v138, s[56:57]
	s_add_u32 s56, s56, 0x15800
	s_addc_u32 s57, s57, 0
	global_load_dwordx4 v[58:61], v138, s[56:57]
	s_add_u32 s56, s56, 0x15800
	s_addc_u32 s57, s57, 0
	global_load_dwordx4 v[62:65], v138, s[56:57]
	s_add_u32 s56, s56, 0x15800
	s_addc_u32 s57, s57, 0
	global_load_dwordx4 v[66:69], v138, s[56:57]
	s_add_u32 s56, s56, 0x51f800
	s_addc_u32 s57, s57, 0
.Lc16_ffn1_nopf_3:
	v_mul_f32_e32 v186, v70, v226
	v_rndne_f32_e32 v186, v186
	v_cvt_i32_f32_e32 v186, v186
	v_mul_f32_e32 v187, v74, v226
	v_rndne_f32_e32 v187, v187
	v_cvt_i32_f32_e32 v187, v187
	v_mul_f32_e32 v188, v78, v226
	v_rndne_f32_e32 v188, v188
	v_cvt_i32_f32_e32 v188, v188
	v_mul_f32_e32 v189, v82, v226
	v_rndne_f32_e32 v189, v189
	v_cvt_i32_f32_e32 v189, v189
	v_and_b32_e32 v186, 0xff, v186
	v_and_b32_e32 v187, 0xff, v187
	v_and_b32_e32 v188, 0xff, v188
	v_lshl_or_b32 v190, v187, 8, v186
	v_lshl_or_b32 v190, v188, 16, v190
	v_lshl_or_b32 v190, v189, 24, v190
	ds_write_b32 v139, v190 offset:256
	v_mul_f32_e32 v186, v71, v227
	v_rndne_f32_e32 v186, v186
	v_cvt_i32_f32_e32 v186, v186
	v_mul_f32_e32 v187, v75, v227
	v_rndne_f32_e32 v187, v187
	v_cvt_i32_f32_e32 v187, v187
	v_mul_f32_e32 v188, v79, v227
	v_rndne_f32_e32 v188, v188
	v_cvt_i32_f32_e32 v188, v188
	v_mul_f32_e32 v189, v83, v227
	v_rndne_f32_e32 v189, v189
	v_cvt_i32_f32_e32 v189, v189
	v_and_b32_e32 v186, 0xff, v186
	v_and_b32_e32 v187, 0xff, v187
	v_and_b32_e32 v188, 0xff, v188
	v_lshl_or_b32 v190, v187, 8, v186
	v_lshl_or_b32 v190, v188, 16, v190
	v_lshl_or_b32 v190, v189, 24, v190
	ds_write_b32 v139, v190 offset:768
	v_mul_f32_e32 v186, v72, v228
	v_rndne_f32_e32 v186, v186
	v_cvt_i32_f32_e32 v186, v186
	v_mul_f32_e32 v187, v76, v228
	v_rndne_f32_e32 v187, v187
	v_cvt_i32_f32_e32 v187, v187
	v_mul_f32_e32 v188, v80, v228
	v_rndne_f32_e32 v188, v188
	v_cvt_i32_f32_e32 v188, v188
	v_mul_f32_e32 v189, v84, v228
	v_rndne_f32_e32 v189, v189
	v_cvt_i32_f32_e32 v189, v189
	v_and_b32_e32 v186, 0xff, v186
	v_and_b32_e32 v187, 0xff, v187
	v_and_b32_e32 v188, 0xff, v188
	v_lshl_or_b32 v190, v187, 8, v186
	v_lshl_or_b32 v190, v188, 16, v190
	v_lshl_or_b32 v190, v189, 24, v190
	ds_write_b32 v139, v190 offset:1280
	v_mul_f32_e32 v186, v73, v229
	v_rndne_f32_e32 v186, v186
	v_cvt_i32_f32_e32 v186, v186
	v_mul_f32_e32 v187, v77, v229
	v_rndne_f32_e32 v187, v187
	v_cvt_i32_f32_e32 v187, v187
	v_mul_f32_e32 v188, v81, v229
	v_rndne_f32_e32 v188, v188
	v_cvt_i32_f32_e32 v188, v188
	v_mul_f32_e32 v189, v85, v229
	v_rndne_f32_e32 v189, v189
	v_cvt_i32_f32_e32 v189, v189
	v_and_b32_e32 v186, 0xff, v186
	v_and_b32_e32 v187, 0xff, v187
	v_and_b32_e32 v188, 0xff, v188
	v_lshl_or_b32 v190, v187, 8, v186
	v_lshl_or_b32 v190, v188, 16, v190
	v_lshl_or_b32 v190, v189, 24, v190
	ds_write_b32 v139, v190 offset:1792
	s_cmp_ge_u32 s10, 0x560
	s_cbranch_scc1 .Lc16_ffn1_nopf_4
	global_load_dwordx4 v[70:73], v138, s[56:57]
	s_add_u32 s56, s56, 0x15800
	s_addc_u32 s57, s57, 0
	global_load_dwordx4 v[74:77], v138, s[56:57]
	s_add_u32 s56, s56, 0x15800
	s_addc_u32 s57, s57, 0
	global_load_dwordx4 v[78:81], v138, s[56:57]
	s_add_u32 s56, s56, 0x15800
	s_addc_u32 s57, s57, 0
	global_load_dwordx4 v[82:85], v138, s[56:57]
	s_add_u32 s56, s56, 0x51f800
	s_addc_u32 s57, s57, 0
.Lc16_ffn1_nopf_4:
	v_mul_f32_e32 v186, v86, v226
	v_rndne_f32_e32 v186, v186
	v_cvt_i32_f32_e32 v186, v186
	v_mul_f32_e32 v187, v90, v226
	v_rndne_f32_e32 v187, v187
	v_cvt_i32_f32_e32 v187, v187
	v_mul_f32_e32 v188, v94, v226
	v_rndne_f32_e32 v188, v188
	v_cvt_i32_f32_e32 v188, v188
	v_mul_f32_e32 v189, v98, v226
	v_rndne_f32_e32 v189, v189
	v_cvt_i32_f32_e32 v189, v189
	v_and_b32_e32 v186, 0xff, v186
	v_and_b32_e32 v187, 0xff, v187
	v_and_b32_e32 v188, 0xff, v188
	v_lshl_or_b32 v190, v187, 8, v186
	v_lshl_or_b32 v190, v188, 16, v190
	v_lshl_or_b32 v190, v189, 24, v190
	ds_write_b32 v139, v190 offset:320
	v_mul_f32_e32 v186, v87, v227
	v_rndne_f32_e32 v186, v186
	v_cvt_i32_f32_e32 v186, v186
	v_mul_f32_e32 v187, v91, v227
	v_rndne_f32_e32 v187, v187
	v_cvt_i32_f32_e32 v187, v187
	v_mul_f32_e32 v188, v95, v227
	v_rndne_f32_e32 v188, v188
	v_cvt_i32_f32_e32 v188, v188
	v_mul_f32_e32 v189, v99, v227
	v_rndne_f32_e32 v189, v189
	v_cvt_i32_f32_e32 v189, v189
	v_and_b32_e32 v186, 0xff, v186
	v_and_b32_e32 v187, 0xff, v187
	v_and_b32_e32 v188, 0xff, v188
	v_lshl_or_b32 v190, v187, 8, v186
	v_lshl_or_b32 v190, v188, 16, v190
	v_lshl_or_b32 v190, v189, 24, v190
	ds_write_b32 v139, v190 offset:832
	v_mul_f32_e32 v186, v88, v228
	v_rndne_f32_e32 v186, v186
	v_cvt_i32_f32_e32 v186, v186
	v_mul_f32_e32 v187, v92, v228
	v_rndne_f32_e32 v187, v187
	v_cvt_i32_f32_e32 v187, v187
	v_mul_f32_e32 v188, v96, v228
	v_rndne_f32_e32 v188, v188
	v_cvt_i32_f32_e32 v188, v188
	v_mul_f32_e32 v189, v100, v228
	v_rndne_f32_e32 v189, v189
	v_cvt_i32_f32_e32 v189, v189
	v_and_b32_e32 v186, 0xff, v186
	v_and_b32_e32 v187, 0xff, v187
	v_and_b32_e32 v188, 0xff, v188
	v_lshl_or_b32 v190, v187, 8, v186
	v_lshl_or_b32 v190, v188, 16, v190
	v_lshl_or_b32 v190, v189, 24, v190
	ds_write_b32 v139, v190 offset:1344
	v_mul_f32_e32 v186, v89, v229
	v_rndne_f32_e32 v186, v186
	v_cvt_i32_f32_e32 v186, v186
	v_mul_f32_e32 v187, v93, v229
	v_rndne_f32_e32 v187, v187
	v_cvt_i32_f32_e32 v187, v187
	v_mul_f32_e32 v188, v97, v229
	v_rndne_f32_e32 v188, v188
	v_cvt_i32_f32_e32 v188, v188
	v_mul_f32_e32 v189, v101, v229
	v_rndne_f32_e32 v189, v189
	v_cvt_i32_f32_e32 v189, v189
	v_and_b32_e32 v186, 0xff, v186
	v_and_b32_e32 v187, 0xff, v187
	v_and_b32_e32 v188, 0xff, v188
	v_lshl_or_b32 v190, v187, 8, v186
	v_lshl_or_b32 v190, v188, 16, v190
	v_lshl_or_b32 v190, v189, 24, v190
	ds_write_b32 v139, v190 offset:1856
	s_cmp_ge_u32 s10, 0x560
	s_cbranch_scc1 .Lc16_ffn1_nopf_5
	global_load_dwordx4 v[86:89], v138, s[56:57]
	s_add_u32 s56, s56, 0x15800
	s_addc_u32 s57, s57, 0
	global_load_dwordx4 v[90:93], v138, s[56:57]
	s_add_u32 s56, s56, 0x15800
	s_addc_u32 s57, s57, 0
	global_load_dwordx4 v[94:97], v138, s[56:57]
	s_add_u32 s56, s56, 0x15800
	s_addc_u32 s57, s57, 0
	global_load_dwordx4 v[98:101], v138, s[56:57]
	s_add_u32 s56, s56, 0x51f800
	s_addc_u32 s57, s57, 0
.Lc16_ffn1_nopf_5:
	v_mul_f32_e32 v186, v102, v226
	v_rndne_f32_e32 v186, v186
	v_cvt_i32_f32_e32 v186, v186
	v_mul_f32_e32 v187, v106, v226
	v_rndne_f32_e32 v187, v187
	v_cvt_i32_f32_e32 v187, v187
	v_mul_f32_e32 v188, v110, v226
	v_rndne_f32_e32 v188, v188
	v_cvt_i32_f32_e32 v188, v188
	v_mul_f32_e32 v189, v114, v226
	v_rndne_f32_e32 v189, v189
	v_cvt_i32_f32_e32 v189, v189
	v_and_b32_e32 v186, 0xff, v186
	v_and_b32_e32 v187, 0xff, v187
	v_and_b32_e32 v188, 0xff, v188
	v_lshl_or_b32 v190, v187, 8, v186
	v_lshl_or_b32 v190, v188, 16, v190
	v_lshl_or_b32 v190, v189, 24, v190
	ds_write_b32 v139, v190 offset:384
	v_mul_f32_e32 v186, v103, v227
	v_rndne_f32_e32 v186, v186
	v_cvt_i32_f32_e32 v186, v186
	v_mul_f32_e32 v187, v107, v227
	v_rndne_f32_e32 v187, v187
	v_cvt_i32_f32_e32 v187, v187
	v_mul_f32_e32 v188, v111, v227
	v_rndne_f32_e32 v188, v188
	v_cvt_i32_f32_e32 v188, v188
	v_mul_f32_e32 v189, v115, v227
	v_rndne_f32_e32 v189, v189
	v_cvt_i32_f32_e32 v189, v189
	v_and_b32_e32 v186, 0xff, v186
	v_and_b32_e32 v187, 0xff, v187
	v_and_b32_e32 v188, 0xff, v188
	v_lshl_or_b32 v190, v187, 8, v186
	v_lshl_or_b32 v190, v188, 16, v190
	v_lshl_or_b32 v190, v189, 24, v190
	ds_write_b32 v139, v190 offset:896
	v_mul_f32_e32 v186, v104, v228
	v_rndne_f32_e32 v186, v186
	v_cvt_i32_f32_e32 v186, v186
	v_mul_f32_e32 v187, v108, v228
	v_rndne_f32_e32 v187, v187
	v_cvt_i32_f32_e32 v187, v187
	v_mul_f32_e32 v188, v112, v228
	v_rndne_f32_e32 v188, v188
	v_cvt_i32_f32_e32 v188, v188
	v_mul_f32_e32 v189, v116, v228
	v_rndne_f32_e32 v189, v189
	v_cvt_i32_f32_e32 v189, v189
	v_and_b32_e32 v186, 0xff, v186
	v_and_b32_e32 v187, 0xff, v187
	v_and_b32_e32 v188, 0xff, v188
	v_lshl_or_b32 v190, v187, 8, v186
	v_lshl_or_b32 v190, v188, 16, v190
	v_lshl_or_b32 v190, v189, 24, v190
	ds_write_b32 v139, v190 offset:1408
	v_mul_f32_e32 v186, v105, v229
	v_rndne_f32_e32 v186, v186
	v_cvt_i32_f32_e32 v186, v186
	v_mul_f32_e32 v187, v109, v229
	v_rndne_f32_e32 v187, v187
	v_cvt_i32_f32_e32 v187, v187
	v_mul_f32_e32 v188, v113, v229
	v_rndne_f32_e32 v188, v188
	v_cvt_i32_f32_e32 v188, v188
	v_mul_f32_e32 v189, v117, v229
	v_rndne_f32_e32 v189, v189
	v_cvt_i32_f32_e32 v189, v189
	v_and_b32_e32 v186, 0xff, v186
	v_and_b32_e32 v187, 0xff, v187
	v_and_b32_e32 v188, 0xff, v188
	v_lshl_or_b32 v190, v187, 8, v186
	v_lshl_or_b32 v190, v188, 16, v190
	v_lshl_or_b32 v190, v189, 24, v190
	ds_write_b32 v139, v190 offset:1920
	s_cmp_ge_u32 s10, 0x560
	s_cbranch_scc1 .Lc16_ffn1_nopf_6
	global_load_dwordx4 v[102:105], v138, s[56:57]
	s_add_u32 s56, s56, 0x15800
	s_addc_u32 s57, s57, 0
	global_load_dwordx4 v[106:109], v138, s[56:57]
	s_add_u32 s56, s56, 0x15800
	s_addc_u32 s57, s57, 0
	global_load_dwordx4 v[110:113], v138, s[56:57]
	s_add_u32 s56, s56, 0x15800
	s_addc_u32 s57, s57, 0
	global_load_dwordx4 v[114:117], v138, s[56:57]
	s_add_u32 s56, s56, 0x51f800
	s_addc_u32 s57, s57, 0
.Lc16_ffn1_nopf_6:
	v_mul_f32_e32 v186, v118, v226
	v_rndne_f32_e32 v186, v186
	v_cvt_i32_f32_e32 v186, v186
	v_mul_f32_e32 v187, v122, v226
	v_rndne_f32_e32 v187, v187
	v_cvt_i32_f32_e32 v187, v187
	v_mul_f32_e32 v188, v126, v226
	v_rndne_f32_e32 v188, v188
	v_cvt_i32_f32_e32 v188, v188
	v_mul_f32_e32 v189, v130, v226
	v_rndne_f32_e32 v189, v189
	v_cvt_i32_f32_e32 v189, v189
	v_and_b32_e32 v186, 0xff, v186
	v_and_b32_e32 v187, 0xff, v187
	v_and_b32_e32 v188, 0xff, v188
	v_lshl_or_b32 v190, v187, 8, v186
	v_lshl_or_b32 v190, v188, 16, v190
	v_lshl_or_b32 v190, v189, 24, v190
	ds_write_b32 v139, v190 offset:448
	v_mul_f32_e32 v186, v119, v227
	v_rndne_f32_e32 v186, v186
	v_cvt_i32_f32_e32 v186, v186
	v_mul_f32_e32 v187, v123, v227
	v_rndne_f32_e32 v187, v187
	v_cvt_i32_f32_e32 v187, v187
	v_mul_f32_e32 v188, v127, v227
	v_rndne_f32_e32 v188, v188
	v_cvt_i32_f32_e32 v188, v188
	v_mul_f32_e32 v189, v131, v227
	v_rndne_f32_e32 v189, v189
	v_cvt_i32_f32_e32 v189, v189
	v_and_b32_e32 v186, 0xff, v186
	v_and_b32_e32 v187, 0xff, v187
	v_and_b32_e32 v188, 0xff, v188
	v_lshl_or_b32 v190, v187, 8, v186
	v_lshl_or_b32 v190, v188, 16, v190
	v_lshl_or_b32 v190, v189, 24, v190
	ds_write_b32 v139, v190 offset:960
	v_mul_f32_e32 v186, v120, v228
	v_rndne_f32_e32 v186, v186
	v_cvt_i32_f32_e32 v186, v186
	v_mul_f32_e32 v187, v124, v228
	v_rndne_f32_e32 v187, v187
	v_cvt_i32_f32_e32 v187, v187
	v_mul_f32_e32 v188, v128, v228
	v_rndne_f32_e32 v188, v188
	v_cvt_i32_f32_e32 v188, v188
	v_mul_f32_e32 v189, v132, v228
	v_rndne_f32_e32 v189, v189
	v_cvt_i32_f32_e32 v189, v189
	v_and_b32_e32 v186, 0xff, v186
	v_and_b32_e32 v187, 0xff, v187
	v_and_b32_e32 v188, 0xff, v188
	v_lshl_or_b32 v190, v187, 8, v186
	v_lshl_or_b32 v190, v188, 16, v190
	v_lshl_or_b32 v190, v189, 24, v190
	ds_write_b32 v139, v190 offset:1472
	v_mul_f32_e32 v186, v121, v229
	v_rndne_f32_e32 v186, v186
	v_cvt_i32_f32_e32 v186, v186
	v_mul_f32_e32 v187, v125, v229
	v_rndne_f32_e32 v187, v187
	v_cvt_i32_f32_e32 v187, v187
	v_mul_f32_e32 v188, v129, v229
	v_rndne_f32_e32 v188, v188
	v_cvt_i32_f32_e32 v188, v188
	v_mul_f32_e32 v189, v133, v229
	v_rndne_f32_e32 v189, v189
	v_cvt_i32_f32_e32 v189, v189
	v_and_b32_e32 v186, 0xff, v186
	v_and_b32_e32 v187, 0xff, v187
	v_and_b32_e32 v188, 0xff, v188
	v_lshl_or_b32 v190, v187, 8, v186
	v_lshl_or_b32 v190, v188, 16, v190
	v_lshl_or_b32 v190, v189, 24, v190
	ds_write_b32 v139, v190 offset:1984
	s_cmp_ge_u32 s10, 0x560
	s_cbranch_scc1 .Lc16_ffn1_nopf_7
	global_load_dwordx4 v[118:121], v138, s[56:57]
	s_add_u32 s56, s56, 0x15800
	s_addc_u32 s57, s57, 0
	global_load_dwordx4 v[122:125], v138, s[56:57]
	s_add_u32 s56, s56, 0x15800
	s_addc_u32 s57, s57, 0
	global_load_dwordx4 v[126:129], v138, s[56:57]
	s_add_u32 s56, s56, 0x15800
	s_addc_u32 s57, s57, 0
	global_load_dwordx4 v[130:133], v138, s[56:57]

.Lc16_mixer_nocm:
	v_div_scale_f32 v175, s[70:71], v220, v220, s74
	v_rcp_f32_e32 v176, v175
	s_nop 0
	v_fma_f32 v177, -v175, v176, 1.0
	v_fmac_f32_e32 v176, v177, v176
	v_div_scale_f32 v177, vcc, s74, v220, s74
	v_mul_f32_e32 v178, v177, v176
	v_fma_f32 v180, -v175, v178, v177
	v_fmac_f32_e32 v178, v180, v176
	v_fma_f32 v175, -v175, v178, v177
	s_nop 0
	v_div_fmas_f32 v175, v175, v176, v178
	v_div_fixup_f32 v175, v175, v220, s74
	v_cmp_lt_f32_e32 vcc, 0, v220
	s_nop 1
	v_cndmask_b32_e32 v226, 0, v175, vcc
	v_div_scale_f32 v175, s[70:71], v221, v221, s74
	v_rcp_f32_e32 v176, v175
	s_nop 0
	v_fma_f32 v177, -v175, v176, 1.0
	v_fmac_f32_e32 v176, v177, v176
	v_div_scale_f32 v177, vcc, s74, v221, s74
	v_mul_f32_e32 v178, v177, v176
	v_fma_f32 v180, -v175, v178, v177
	v_fmac_f32_e32 v178, v180, v176
	v_fma_f32 v175, -v175, v178, v177
	s_nop 0
	v_div_fmas_f32 v175, v175, v176, v178
	v_div_fixup_f32 v175, v175, v221, s74
	v_cmp_lt_f32_e32 vcc, 0, v221
	s_nop 1
	v_cndmask_b32_e32 v227, 0, v175, vcc
	v_div_scale_f32 v175, s[70:71], v222, v222, s74
	v_rcp_f32_e32 v176, v175
	s_nop 0
	v_fma_f32 v177, -v175, v176, 1.0
	v_fmac_f32_e32 v176, v177, v176
	v_div_scale_f32 v177, vcc, s74, v222, s74
	v_mul_f32_e32 v178, v177, v176
	v_fma_f32 v180, -v175, v178, v177
	v_fmac_f32_e32 v178, v180, v176
	v_fma_f32 v175, -v175, v178, v177
	s_nop 0
	v_div_fmas_f32 v175, v175, v176, v178
	v_div_fixup_f32 v175, v175, v222, s74
	v_cmp_lt_f32_e32 vcc, 0, v222
	s_nop 1
	v_cndmask_b32_e32 v228, 0, v175, vcc
	v_div_scale_f32 v175, s[70:71], v223, v223, s74
	v_rcp_f32_e32 v176, v175
	s_nop 0
	v_fma_f32 v177, -v175, v176, 1.0
	v_fmac_f32_e32 v176, v177, v176
	v_div_scale_f32 v177, vcc, s74, v223, s74
	v_mul_f32_e32 v178, v177, v176
	v_fma_f32 v180, -v175, v178, v177
	v_fmac_f32_e32 v178, v180, v176
	v_fma_f32 v175, -v175, v178, v177
	s_nop 0
	v_div_fmas_f32 v175, v175, v176, v178
	v_div_fixup_f32 v175, v175, v223, s74
	v_cmp_lt_f32_e32 vcc, 0, v223
	s_nop 1
	v_cndmask_b32_e32 v229, 0, v175, vcc
	s_lshl_b32 s3, s2, 13
	s_lshl_b32 s10, s1, 10
	s_add_u32 s3, s3, s10
	s_add_u32 s36, s34, s3
	s_addc_u32 s37, s35, 0
	s_add_u32 s36, s36, 0x3f400000
	s_addc_u32 s37, s37, 0
	s_add_u32 s38, s36, 0x2000
	s_addc_u32 s39, s37, 0
	s_add_u32 s78, s38, 0x2000
	s_addc_u32 s79, s39, 0
	s_add_u32 s80, s78, 0x2000
	s_addc_u32 s81, s79, 0
	s_add_u32 s10, s0, s33
	s_lshl_b32 s3, s10, 6
	s_add_u32 s56, s48, s3
	s_addc_u32 s57, s49, 0
	s_cmp_ge_u32 s2, 0x1800
	s_cbranch_scc1 .Lc16_mixer_nobf_0
	v_cvt_pk_bf16_f32 v236, v6, v10
	v_cvt_pk_bf16_f32 v237, v14, v18
	global_store_dwordx2 v231, v[236:237], s[36:37] offset:0
	v_cvt_pk_bf16_f32 v238, v7, v11
	v_cvt_pk_bf16_f32 v239, v15, v19
	global_store_dwordx2 v231, v[238:239], s[38:39] offset:0
	v_cvt_pk_bf16_f32 v236, v8, v12
	v_cvt_pk_bf16_f32 v237, v16, v20
	global_store_dwordx2 v231, v[236:237], s[78:79] offset:0
	v_cvt_pk_bf16_f32 v238, v9, v13
	v_cvt_pk_bf16_f32 v239, v17, v21
	global_store_dwordx2 v231, v[238:239], s[80:81] offset:0
.Lc16_mixer_nobf_0:
	v_mul_f32_e32 v186, v6, v226
	v_rndne_f32_e32 v186, v186
	v_cvt_i32_f32_e32 v186, v186
	v_mul_f32_e32 v187, v10, v226
	v_rndne_f32_e32 v187, v187
	v_cvt_i32_f32_e32 v187, v187
	v_mul_f32_e32 v188, v14, v226
	v_rndne_f32_e32 v188, v188
	v_cvt_i32_f32_e32 v188, v188
	v_mul_f32_e32 v189, v18, v226
	v_rndne_f32_e32 v189, v189
	v_cvt_i32_f32_e32 v189, v189
	v_and_b32_e32 v186, 0xff, v186
	v_and_b32_e32 v187, 0xff, v187
	v_and_b32_e32 v188, 0xff, v188
	v_lshl_or_b32 v190, v187, 8, v186
	v_lshl_or_b32 v190, v188, 16, v190
	v_lshl_or_b32 v190, v189, 24, v190
	ds_write_b32 v139, v190 offset:0
	v_mul_f32_e32 v186, v7, v227
	v_rndne_f32_e32 v186, v186
	v_cvt_i32_f32_e32 v186, v186
	v_mul_f32_e32 v187, v11, v227
	v_rndne_f32_e32 v187, v187
	v_cvt_i32_f32_e32 v187, v187
	v_mul_f32_e32 v188, v15, v227
	v_rndne_f32_e32 v188, v188
	v_cvt_i32_f32_e32 v188, v188
	v_mul_f32_e32 v189, v19, v227
	v_rndne_f32_e32 v189, v189
	v_cvt_i32_f32_e32 v189, v189
	v_and_b32_e32 v186, 0xff, v186
	v_and_b32_e32 v187, 0xff, v187
	v_and_b32_e32 v188, 0xff, v188
	v_lshl_or_b32 v190, v187, 8, v186
	v_lshl_or_b32 v190, v188, 16, v190
	v_lshl_or_b32 v190, v189, 24, v190
	ds_write_b32 v139, v190 offset:512
	v_mul_f32_e32 v186, v8, v228
	v_rndne_f32_e32 v186, v186
	v_cvt_i32_f32_e32 v186, v186
	v_mul_f32_e32 v187, v12, v228
	v_rndne_f32_e32 v187, v187
	v_cvt_i32_f32_e32 v187, v187
	v_mul_f32_e32 v188, v16, v228
	v_rndne_f32_e32 v188, v188
	v_cvt_i32_f32_e32 v188, v188
	v_mul_f32_e32 v189, v20, v228
	v_rndne_f32_e32 v189, v189
	v_cvt_i32_f32_e32 v189, v189
	v_and_b32_e32 v186, 0xff, v186
	v_and_b32_e32 v187, 0xff, v187
	v_and_b32_e32 v188, 0xff, v188
	v_lshl_or_b32 v190, v187, 8, v186
	v_lshl_or_b32 v190, v188, 16, v190
	v_lshl_or_b32 v190, v189, 24, v190
	ds_write_b32 v139, v190 offset:1024
	v_mul_f32_e32 v186, v9, v229
	v_rndne_f32_e32 v186, v186
	v_cvt_i32_f32_e32 v186, v186
	v_mul_f32_e32 v187, v13, v229
	v_rndne_f32_e32 v187, v187
	v_cvt_i32_f32_e32 v187, v187
	v_mul_f32_e32 v188, v17, v229
	v_rndne_f32_e32 v188, v188
	v_cvt_i32_f32_e32 v188, v188
	v_mul_f32_e32 v189, v21, v229
	v_rndne_f32_e32 v189, v189
	v_cvt_i32_f32_e32 v189, v189
	v_and_b32_e32 v186, 0xff, v186
	v_and_b32_e32 v187, 0xff, v187
	v_and_b32_e32 v188, 0xff, v188
	v_lshl_or_b32 v190, v187, 8, v186
	v_lshl_or_b32 v190, v188, 16, v190
	v_lshl_or_b32 v190, v189, 24, v190
	ds_write_b32 v139, v190 offset:1536
	s_cmp_ge_u32 s10, 0x280
	s_cbranch_scc1 .Lc16_mixer_nopf_0
	global_load_dwordx4 v[6:9], v138, s[56:57]
	s_add_u32 s56, s56, 0xa000
	s_addc_u32 s57, s57, 0
	global_load_dwordx4 v[10:13], v138, s[56:57]
	s_add_u32 s56, s56, 0xa000
	s_addc_u32 s57, s57, 0
	global_load_dwordx4 v[14:17], v138, s[56:57]
	s_add_u32 s56, s56, 0xa000
	s_addc_u32 s57, s57, 0
	global_load_dwordx4 v[18:21], v138, s[56:57]
	s_add_u32 s56, s56, 0x262000
	s_addc_u32 s57, s57, 0
.Lc16_mixer_nopf_0:
	s_cmp_ge_u32 s2, 0x1800
	s_cbranch_scc1 .Lc16_mixer_nobf_1
	v_cvt_pk_bf16_f32 v236, v22, v26
	v_cvt_pk_bf16_f32 v237, v30, v34
	global_store_dwordx2 v231, v[236:237], s[36:37] offset:128
	v_cvt_pk_bf16_f32 v238, v23, v27
	v_cvt_pk_bf16_f32 v239, v31, v35
	global_store_dwordx2 v231, v[238:239], s[38:39] offset:128
	v_cvt_pk_bf16_f32 v236, v24, v28
	v_cvt_pk_bf16_f32 v237, v32, v36
	global_store_dwordx2 v231, v[236:237], s[78:79] offset:128
	v_cvt_pk_bf16_f32 v238, v25, v29
	v_cvt_pk_bf16_f32 v239, v33, v37
	global_store_dwordx2 v231, v[238:239], s[80:81] offset:128

.Lc16_mixer_nopf_1:
	s_cmp_ge_u32 s2, 0x1800
	s_cbranch_scc1 .Lc16_mixer_nobf_2
	v_cvt_pk_bf16_f32 v236, v38, v42
	v_cvt_pk_bf16_f32 v237, v46, v50
	global_store_dwordx2 v231, v[236:237], s[36:37] offset:256
	v_cvt_pk_bf16_f32 v238, v39, v43
	v_cvt_pk_bf16_f32 v239, v47, v51
	global_store_dwordx2 v231, v[238:239], s[38:39] offset:256
	v_cvt_pk_bf16_f32 v236, v40, v44
	v_cvt_pk_bf16_f32 v237, v48, v52
	global_store_dwordx2 v231, v[236:237], s[78:79] offset:256
	v_cvt_pk_bf16_f32 v238, v41, v45
	v_cvt_pk_bf16_f32 v239, v49, v53
	global_store_dwordx2 v231, v[238:239], s[80:81] offset:256

.Lc16_mixer_nopf_2:
	s_cmp_ge_u32 s2, 0x1800
	s_cbranch_scc1 .Lc16_mixer_nobf_3
	v_cvt_pk_bf16_f32 v236, v54, v58
	v_cvt_pk_bf16_f32 v237, v62, v66
	global_store_dwordx2 v231, v[236:237], s[36:37] offset:384
	v_cvt_pk_bf16_f32 v238, v55, v59
	v_cvt_pk_bf16_f32 v239, v63, v67
	global_store_dwordx2 v231, v[238:239], s[38:39] offset:384
	v_cvt_pk_bf16_f32 v236, v56, v60
	v_cvt_pk_bf16_f32 v237, v64, v68
	global_store_dwordx2 v231, v[236:237], s[78:79] offset:384
	v_cvt_pk_bf16_f32 v238, v57, v61
	v_cvt_pk_bf16_f32 v239, v65, v69
	global_store_dwordx2 v231, v[238:239], s[80:81] offset:384

.Lc16_mixer_nopf_3:
	s_cmp_ge_u32 s2, 0x1800
	s_cbranch_scc1 .Lc16_mixer_nobf_4
	v_cvt_pk_bf16_f32 v236, v70, v74
	v_cvt_pk_bf16_f32 v237, v78, v82
	global_store_dwordx2 v231, v[236:237], s[36:37] offset:512
	v_cvt_pk_bf16_f32 v238, v71, v75
	v_cvt_pk_bf16_f32 v239, v79, v83
	global_store_dwordx2 v231, v[238:239], s[38:39] offset:512
	v_cvt_pk_bf16_f32 v236, v72, v76
	v_cvt_pk_bf16_f32 v237, v80, v84
	global_store_dwordx2 v231, v[236:237], s[78:79] offset:512
	v_cvt_pk_bf16_f32 v238, v73, v77
	v_cvt_pk_bf16_f32 v239, v81, v85
	global_store_dwordx2 v231, v[238:239], s[80:81] offset:512

.Lc16_mixer_nopf_4:
	s_cmp_ge_u32 s2, 0x1800
	s_cbranch_scc1 .Lc16_mixer_nobf_5
	v_cvt_pk_bf16_f32 v236, v86, v90
	v_cvt_pk_bf16_f32 v237, v94, v98
	global_store_dwordx2 v231, v[236:237], s[36:37] offset:640
	v_cvt_pk_bf16_f32 v238, v87, v91
	v_cvt_pk_bf16_f32 v239, v95, v99
	global_store_dwordx2 v231, v[238:239], s[38:39] offset:640
	v_cvt_pk_bf16_f32 v236, v88, v92
	v_cvt_pk_bf16_f32 v237, v96, v100
	global_store_dwordx2 v231, v[236:237], s[78:79] offset:640
	v_cvt_pk_bf16_f32 v238, v89, v93
	v_cvt_pk_bf16_f32 v239, v97, v101
	global_store_dwordx2 v231, v[238:239], s[80:81] offset:640

.Lc16_mixer_nopf_5:
	s_cmp_ge_u32 s2, 0x1800
	s_cbranch_scc1 .Lc16_mixer_nobf_6
	v_cvt_pk_bf16_f32 v236, v102, v106
	v_cvt_pk_bf16_f32 v237, v110, v114
	global_store_dwordx2 v231, v[236:237], s[36:37] offset:768
	v_cvt_pk_bf16_f32 v238, v103, v107
	v_cvt_pk_bf16_f32 v239, v111, v115
	global_store_dwordx2 v231, v[238:239], s[38:39] offset:768
	v_cvt_pk_bf16_f32 v236, v104, v108
	v_cvt_pk_bf16_f32 v237, v112, v116
	global_store_dwordx2 v231, v[236:237], s[78:79] offset:768
	v_cvt_pk_bf16_f32 v238, v105, v109
	v_cvt_pk_bf16_f32 v239, v113, v117
	global_store_dwordx2 v231, v[238:239], s[80:81] offset:768

.Lc16_mixer_nopf_6:
	s_cmp_ge_u32 s2, 0x1800
	s_cbranch_scc1 .Lc16_mixer_nobf_7
	v_cvt_pk_bf16_f32 v236, v118, v122
	v_cvt_pk_bf16_f32 v237, v126, v130
	global_store_dwordx2 v231, v[236:237], s[36:37] offset:896
	v_cvt_pk_bf16_f32 v238, v119, v123
	v_cvt_pk_bf16_f32 v239, v127, v131
	global_store_dwordx2 v231, v[238:239], s[38:39] offset:896
	v_cvt_pk_bf16_f32 v236, v120, v124
	v_cvt_pk_bf16_f32 v237, v128, v132
	global_store_dwordx2 v231, v[236:237], s[78:79] offset:896
	v_cvt_pk_bf16_f32 v238, v121, v125
	v_cvt_pk_bf16_f32 v239, v129, v133
	global_store_dwordx2 v231, v[238:239], s[80:81] offset:896

.LBB0_110:
	s_andn2_b64 vcc, exec, s[0:1]
	s_branch .LBB0_112
	s_and_b32 s0, 0xffff, s73
	s_mul_hi_u32 s0, s0, 0x2aaaaab
	s_mul_i32 s5, s0, 0x1800
	s_mul_i32 s0, s4, 0xaaab
	s_add_i32 s0, s0, 0xf2aaa400
	s_add_i32 s7, s23, s81
	v_readlane_b32 s48, v255, 23
	s_lshr_b32 s6, s0, 22
	s_sub_i32 s0, s7, s5
	v_readlane_b32 s52, v255, 27
	v_readlane_b32 s53, v255, 28
	s_add_i32 s0, s0, 0xfffb0000
	v_lshl_add_u32 v2, s6, 6, v135
	v_mov_b64_e32 v[0:1], s[52:53]
	v_mad_i64_i32 v[0:1], s[2:3], v2, s80, v[0:1]
	s_ashr_i32 s1, s0, 31
	v_lshl_add_u64 v[0:1], s[0:1], 2, v[0:1]
	v_lshl_add_u64 v[56:57], v[0:1], 0, v[114:115]
	v_add_co_u32_e32 v4, vcc, s80, v56
	s_mov_b32 s0, 0x50000
	s_nop 0
	v_addc_co_u32_e32 v5, vcc, 0, v57, vcc
	v_add_co_u32_e32 v8, vcc, s0, v56
	s_mov_b32 s0, 0x5a000
	s_nop 0
	v_addc_co_u32_e32 v9, vcc, 0, v57, vcc
	v_add_co_u32_e32 v12, vcc, s0, v56
	s_mov_b32 s0, 0xf0000
	s_nop 0
	v_addc_co_u32_e32 v13, vcc, 0, v57, vcc
	v_add_co_u32_e32 v16, vcc, s95, v56
	global_load_dwordx4 v[0:3], v[56:57], off nt
	s_nop 0
	global_load_dwordx4 v[4:7], v[4:5], off nt
	v_addc_co_u32_e32 v17, vcc, 0, v57, vcc
	v_add_co_u32_e32 v20, vcc, s74, v56
	global_load_dwordx4 v[8:11], v[8:9], off nt
	s_nop 0
	global_load_dwordx4 v[12:15], v[12:13], off nt
	v_addc_co_u32_e32 v21, vcc, 0, v57, vcc
	v_add_co_u32_e32 v24, vcc, s0, v56
	s_mov_b32 s0, 0xfa000
	s_nop 0
	v_addc_co_u32_e32 v25, vcc, 0, v57, vcc
	v_add_co_u32_e32 v28, vcc, s0, v56
	s_mov_b32 s0, 0x19a000
	s_nop 0
	v_addc_co_u32_e32 v29, vcc, 0, v57, vcc
	v_add_co_u32_e32 v32, vcc, s78, v56
	global_load_dwordx4 v[16:19], v[16:17], off nt
	s_nop 0
	global_load_dwordx4 v[20:23], v[20:21], off nt
	v_addc_co_u32_e32 v33, vcc, 0, v57, vcc
	v_add_co_u32_e32 v36, vcc, s84, v56
	global_load_dwordx4 v[24:27], v[24:25], off nt
	s_nop 0
	global_load_dwordx4 v[28:31], v[28:29], off nt
	v_addc_co_u32_e32 v37, vcc, 0, v57, vcc
	v_add_co_u32_e32 v40, vcc, s91, v56
	global_load_dwordx4 v[32:35], v[32:33], off nt
	s_nop 0
	global_load_dwordx4 v[36:39], v[36:37], off nt
	v_addc_co_u32_e32 v41, vcc, 0, v57, vcc
	v_add_co_u32_e32 v44, vcc, s0, v56
	s_mov_b32 s0, 0x230000
	s_nop 0
	v_addc_co_u32_e32 v45, vcc, 0, v57, vcc
	v_add_co_u32_e32 v48, vcc, s16, v56
	global_load_dwordx4 v[40:43], v[40:41], off nt
	s_nop 0
	global_load_dwordx4 v[44:47], v[44:45], off nt
	v_addc_co_u32_e32 v49, vcc, 0, v57, vcc
	v_add_co_u32_e32 v52, vcc, s75, v56
	v_subrev_u32_e32 v64, s5, v163
	s_nop 0
	v_addc_co_u32_e32 v53, vcc, 0, v57, vcc
	v_add_co_u32_e32 v58, vcc, s0, v56
	s_mov_b32 s0, 0x23a000
	s_nop 0
	v_addc_co_u32_e32 v59, vcc, 0, v57, vcc
	global_load_dwordx4 v[48:51], v[48:49], off nt
	s_nop 0
	global_load_dwordx4 v[52:55], v[52:53], off nt
	v_add_co_u32_e32 v60, vcc, s0, v56
	s_lshl_b32 s10, s6, 7
	s_nop 0
	v_addc_co_u32_e32 v61, vcc, 0, v57, vcc
	global_load_dwordx4 v[56:59], v[58:59], off nt
	s_nop 0
	global_load_dwordx4 v[60:63], v[60:61], off nt
	v_readlane_b32 s49, v255, 24
	v_readlane_b32 s50, v255, 25
	v_readlane_b32 s51, v255, 26
	v_readlane_b32 s54, v255, 29
	v_readlane_b32 s55, v255, 30
	v_readlane_b32 s56, v255, 31
	v_readlane_b32 s57, v255, 32
	v_readlane_b32 s58, v255, 33
	v_readlane_b32 s59, v255, 34
	v_readlane_b32 s60, v255, 35
	v_readlane_b32 s61, v255, 36
	v_readlane_b32 s62, v255, 37
	v_readlane_b32 s63, v255, 38
	s_waitcnt vmcnt(14)
	v_cvt_pk_bf16_f32 v0, v0, v4
	v_add_u32_e32 v4, v137, v138
	v_cvt_pk_bf16_f32 v1, v1, v5
	ds_write2_b32 v4, v0, v1 offset1:32
	v_cvt_pk_bf16_f32 v0, v2, v6
	v_cvt_pk_bf16_f32 v1, v3, v7
	ds_write2_b32 v4, v0, v1 offset0:64 offset1:96
	s_waitcnt vmcnt(12)
	v_cvt_pk_bf16_f32 v0, v8, v12
	v_add_u32_e32 v1, v139, v138
	v_cvt_pk_bf16_f32 v2, v9, v13
	ds_write2_b32 v1, v0, v2 offset1:32
	v_cvt_pk_bf16_f32 v0, v10, v14
	v_cvt_pk_bf16_f32 v2, v11, v15
	ds_write2_b32 v1, v0, v2 offset0:64 offset1:96
	v_add_u32_e32 v1, v140, v138
	v_add_u32_e32 v10, s7, v64
	v_subrev_u32_e32 v4, 32, v10
	v_ashrrev_i32_e32 v5, 31, v4
	v_lshl_add_u64 v[8:9], v[128:129], 0, s[10:11]
	v_lshlrev_b64 v[4:5], 13, v[4:5]
	s_waitcnt vmcnt(10)
	v_cvt_pk_bf16_f32 v0, v16, v20
	v_cvt_pk_bf16_f32 v2, v17, v21
	ds_write2_b32 v1, v0, v2 offset1:32
	v_cvt_pk_bf16_f32 v0, v18, v22
	v_cvt_pk_bf16_f32 v2, v19, v23
	ds_write2_b32 v1, v0, v2 offset0:64 offset1:96
	s_waitcnt vmcnt(8)
	v_cvt_pk_bf16_f32 v0, v24, v28
	v_add_u32_e32 v1, v141, v138
	v_cvt_pk_bf16_f32 v2, v25, v29
	ds_write2_b32 v1, v0, v2 offset1:32
	v_cvt_pk_bf16_f32 v0, v26, v30
	v_cvt_pk_bf16_f32 v2, v27, v31
	ds_write2_b32 v1, v0, v2 offset0:64 offset1:96
	s_waitcnt vmcnt(6)
	v_cvt_pk_bf16_f32 v0, v32, v36
	v_add_u32_e32 v1, v142, v138
	v_cvt_pk_bf16_f32 v2, v33, v37
	ds_write2_b32 v1, v0, v2 offset1:32
	v_cvt_pk_bf16_f32 v0, v34, v38
	v_cvt_pk_bf16_f32 v2, v35, v39
	ds_write2_b32 v1, v0, v2 offset0:64 offset1:96
	s_waitcnt vmcnt(4)
	v_cvt_pk_bf16_f32 v0, v40, v44
	v_add_u32_e32 v1, v143, v138
	v_cvt_pk_bf16_f32 v2, v41, v45
	ds_write2_b32 v1, v0, v2 offset1:32
	v_cvt_pk_bf16_f32 v0, v42, v46
	v_cvt_pk_bf16_f32 v2, v43, v47
	ds_write2_b32 v1, v0, v2 offset0:64 offset1:96
	v_add_u32_e32 v1, v144, v138
	v_lshl_add_u64 v[12:13], v[8:9], 0, v[4:5]
	v_ashrrev_i32_e32 v11, 31, v10
	s_waitcnt vmcnt(2)
	v_cvt_pk_bf16_f32 v0, v48, v52
	v_cvt_pk_bf16_f32 v2, v49, v53
	ds_write2_b32 v1, v0, v2 offset1:32
	v_cvt_pk_bf16_f32 v0, v50, v54
	v_cvt_pk_bf16_f32 v2, v51, v55
	ds_write2_b32 v1, v0, v2 offset0:64 offset1:96
	s_waitcnt vmcnt(0)
	v_cvt_pk_bf16_f32 v0, v56, v60
	v_add_u32_e32 v1, v145, v138
	v_cvt_pk_bf16_f32 v2, v57, v61
	ds_write2_b32 v1, v0, v2 offset1:32
	v_cvt_pk_bf16_f32 v0, v58, v62
	v_cvt_pk_bf16_f32 v2, v59, v63
	ds_write2_b32 v1, v0, v2 offset0:64 offset1:96
	s_waitcnt lgkmcnt(0)
	ds_read_b128 v[0:3], v147
	ds_read_b128 v[4:7], v149
	s_waitcnt lgkmcnt(1)
	global_store_dwordx4 v[12:13], v[0:3], off
	s_nop 1
	v_subrev_u32_e32 v0, 24, v10
	v_ashrrev_i32_e32 v1, 31, v0
	v_lshlrev_b64 v[0:1], 13, v[0:1]
	v_lshl_add_u64 v[0:1], v[8:9], 0, v[0:1]
	s_waitcnt lgkmcnt(0)
	global_store_dwordx4 v[0:1], v[4:7], off
	ds_read_b128 v[0:3], v151
	s_nop 0
	v_add_u32_e32 v4, -16, v10
	v_ashrrev_i32_e32 v5, 31, v4
	v_lshlrev_b64 v[4:5], 13, v[4:5]
	v_lshl_add_u64 v[12:13], v[8:9], 0, v[4:5]
	ds_read_b128 v[4:7], v153
	s_waitcnt lgkmcnt(1)
	global_store_dwordx4 v[12:13], v[0:3], off
	s_nop 1
	v_add_u32_e32 v0, -8, v10
	v_ashrrev_i32_e32 v1, 31, v0
	v_lshlrev_b64 v[0:1], 13, v[0:1]
	v_lshl_add_u64 v[0:1], v[8:9], 0, v[0:1]
	s_waitcnt lgkmcnt(0)
	global_store_dwordx4 v[0:1], v[4:7], off
	ds_read_b128 v[0:3], v155
	s_nop 0
	v_lshlrev_b64 v[4:5], 13, v[10:11]
	v_lshl_add_u64 v[12:13], v[8:9], 0, v[4:5]
	ds_read_b128 v[4:7], v157
	s_waitcnt lgkmcnt(1)
	global_store_dwordx4 v[12:13], v[0:3], off
	s_nop 1
	v_add_u32_e32 v0, 8, v10
	v_ashrrev_i32_e32 v1, 31, v0
	v_lshlrev_b64 v[0:1], 13, v[0:1]
	v_lshl_add_u64 v[0:1], v[8:9], 0, v[0:1]
	s_waitcnt lgkmcnt(0)
	global_store_dwordx4 v[0:1], v[4:7], off
	ds_read_b128 v[0:3], v159
	s_nop 0
	v_add_u32_e32 v4, 16, v10
	v_ashrrev_i32_e32 v5, 31, v4
	v_lshlrev_b64 v[4:5], 13, v[4:5]
	v_lshl_add_u64 v[12:13], v[8:9], 0, v[4:5]
	ds_read_b128 v[4:7], v161
	s_waitcnt lgkmcnt(1)
	global_store_dwordx4 v[12:13], v[0:3], off
	s_nop 1
	v_add_u32_e32 v0, 24, v10
	v_ashrrev_i32_e32 v1, 31, v0
	v_lshlrev_b64 v[0:1], 13, v[0:1]
	v_lshl_add_u64 v[0:1], v[8:9], 0, v[0:1]
	s_waitcnt lgkmcnt(0)
	global_store_dwordx4 v[0:1], v[4:7], off
	s_waitcnt lgkmcnt(0)

.LBB0_484:
	v_mbcnt_lo_u32_b32 v135, -1, 0
	v_mbcnt_hi_u32_b32 v135, -1, v135
	v_lshrrev_b32_e32 v136, 2, v135
	v_and_b32_e32 v137, 3, v135
	v_lshlrev_b32_e32 v230, 4, v137
	v_lshlrev_b32_e32 v231, 15, v137
	v_lshl_add_u32 v231, v136, 3, v231
	v_readlane_b32 s7, v254, 17
	v_readlane_b32 s1, v254, 16
	v_readlane_b32 s13, v254, 15
	s_mov_b32 s11, 0x42fe0000
	s_mov_b32 s5, 0
	v_lshlrev_b32_e32 v139, 11, v137
	v_lshl_add_u32 v139, v136, 2, v139
	s_nop 1
	v_add_u32_e32 v139, s7, v139
	v_lshlrev_b32_e32 v174, 2, v135
	v_xor_b32_e32 v192, 0x10, v174
	v_xor_b32_e32 v193, 0x20, v174
	v_xor_b32_e32 v194, 0x40, v174
	v_xor_b32_e32 v195, 0x80, v174
	v_lshrrev_b32_e32 v175, 5, v135
	v_and_b32_e32 v176, 31, v135
	v_lshlrev_b32_e32 v212, 9, v175
	v_lshl_add_u32 v212, v176, 4, v212
	v_add_u32_e32 v212, s7, v212
	v_lshlrev_b32_e32 v213, 12, v175
	v_lshl_add_u32 v213, v176, 4, v213
	v_readlane_b32 s52, v255, 61
	v_readlane_b32 s53, v255, 62
	v_mul_u32_u24_e32 v138, 0x56000, v136
	v_lshl_add_u32 v138, v137, 4, v138
	s_mul_i32 s3, s1, 0x2b00000
	s_nop 1
	s_add_u32 s52, s52, s3
	s_addc_u32 s53, s53, 0
	s_mov_b32 s0, s13
	s_cmp_ge_u32 s0, 0x560
	s_cbranch_scc1 .Lc16p3_ffn2_done
	s_lshl_b32 s3, s0, 6
	s_add_u32 s54, s52, s3
	s_addc_u32 s55, s53, 0
	global_load_dwordx4 v[6:9], v138, s[54:55]
	s_add_u32 s54, s54, 0x15800
	s_addc_u32 s55, s55, 0
	global_load_dwordx4 v[10:13], v138, s[54:55]
	s_add_u32 s54, s54, 0x15800
	s_addc_u32 s55, s55, 0
	global_load_dwordx4 v[14:17], v138, s[54:55]
	s_add_u32 s54, s54, 0x15800
	s_addc_u32 s55, s55, 0
	global_load_dwordx4 v[18:21], v138, s[54:55]
	s_add_u32 s54, s54, 0x51f800
	s_addc_u32 s55, s55, 0
	global_load_dwordx4 v[22:25], v138, s[54:55]
	s_add_u32 s54, s54, 0x15800
	s_addc_u32 s55, s55, 0
	global_load_dwordx4 v[26:29], v138, s[54:55]
	s_add_u32 s54, s54, 0x15800
	s_addc_u32 s55, s55, 0
	global_load_dwordx4 v[30:33], v138, s[54:55]
	s_add_u32 s54, s54, 0x15800
	s_addc_u32 s55, s55, 0
	global_load_dwordx4 v[34:37], v138, s[54:55]
	s_add_u32 s54, s54, 0x51f800
	s_addc_u32 s55, s55, 0
	global_load_dwordx4 v[38:41], v138, s[54:55]
	s_add_u32 s54, s54, 0x15800
	s_addc_u32 s55, s55, 0
	global_load_dwordx4 v[42:45], v138, s[54:55]
	s_add_u32 s54, s54, 0x15800
	s_addc_u32 s55, s55, 0
	global_load_dwordx4 v[46:49], v138, s[54:55]
	s_add_u32 s54, s54, 0x15800
	s_addc_u32 s55, s55, 0
	global_load_dwordx4 v[50:53], v138, s[54:55]
	s_add_u32 s54, s54, 0x51f800
	s_addc_u32 s55, s55, 0
	global_load_dwordx4 v[54:57], v138, s[54:55]
	s_add_u32 s54, s54, 0x15800
	s_addc_u32 s55, s55, 0
	global_load_dwordx4 v[58:61], v138, s[54:55]
	s_add_u32 s54, s54, 0x15800
	s_addc_u32 s55, s55, 0
	global_load_dwordx4 v[62:65], v138, s[54:55]
	s_add_u32 s54, s54, 0x15800
	s_addc_u32 s55, s55, 0
	global_load_dwordx4 v[66:69], v138, s[54:55]
	s_add_u32 s54, s54, 0x51f800
	s_addc_u32 s55, s55, 0
	global_load_dwordx4 v[70:73], v138, s[54:55]
	s_add_u32 s54, s54, 0x15800
	s_addc_u32 s55, s55, 0
	global_load_dwordx4 v[74:77], v138, s[54:55]
	s_add_u32 s54, s54, 0x15800
	s_addc_u32 s55, s55, 0
	global_load_dwordx4 v[78:81], v138, s[54:55]
	s_add_u32 s54, s54, 0x15800
	s_addc_u32 s55, s55, 0
	global_load_dwordx4 v[82:85], v138, s[54:55]
	s_add_u32 s54, s54, 0x51f800
	s_addc_u32 s55, s55, 0
	global_load_dwordx4 v[86:89], v138, s[54:55]
	s_add_u32 s54, s54, 0x15800
	s_addc_u32 s55, s55, 0
	global_load_dwordx4 v[90:93], v138, s[54:55]
	s_add_u32 s54, s54, 0x15800
	s_addc_u32 s55, s55, 0
	global_load_dwordx4 v[94:97], v138, s[54:55]
	s_add_u32 s54, s54, 0x15800
	s_addc_u32 s55, s55, 0
	global_load_dwordx4 v[98:101], v138, s[54:55]
	s_add_u32 s54, s54, 0x51f800
	s_addc_u32 s55, s55, 0
	global_load_dwordx4 v[102:105], v138, s[54:55]
	s_add_u32 s54, s54, 0x15800
	s_addc_u32 s55, s55, 0
	global_load_dwordx4 v[106:109], v138, s[54:55]
	s_add_u32 s54, s54, 0x15800
	s_addc_u32 s55, s55, 0
	global_load_dwordx4 v[110:113], v138, s[54:55]
	s_add_u32 s54, s54, 0x15800
	s_addc_u32 s55, s55, 0
	global_load_dwordx4 v[114:117], v138, s[54:55]
	s_add_u32 s54, s54, 0x51f800
	s_addc_u32 s55, s55, 0
	global_load_dwordx4 v[118:121], v138, s[54:55]
	s_add_u32 s54, s54, 0x15800
	s_addc_u32 s55, s55, 0
	global_load_dwordx4 v[122:125], v138, s[54:55]
	s_add_u32 s54, s54, 0x15800
	s_addc_u32 s55, s55, 0
	global_load_dwordx4 v[126:129], v138, s[54:55]
	s_add_u32 s54, s54, 0x15800
	s_addc_u32 s55, s55, 0
	global_load_dwordx4 v[130:133], v138, s[54:55]

.Lc16p3_ffn2_nocm:
	v_div_scale_f32 v175, s[58:59], v220, v220, s11
	v_rcp_f32_e32 v176, v175
	s_nop 0
	v_fma_f32 v177, -v175, v176, 1.0
	v_fmac_f32_e32 v176, v177, v176
	v_div_scale_f32 v177, vcc, s11, v220, s11
	v_mul_f32_e32 v178, v177, v176
	v_fma_f32 v180, -v175, v178, v177
	v_fmac_f32_e32 v178, v180, v176
	v_fma_f32 v175, -v175, v178, v177
	s_nop 0
	v_div_fmas_f32 v175, v175, v176, v178
	v_div_fixup_f32 v175, v175, v220, s11
	v_cmp_lt_f32_e32 vcc, 0, v220
	s_nop 1
	v_cndmask_b32_e32 v226, 0, v175, vcc
	v_div_scale_f32 v175, s[58:59], v221, v221, s11
	v_rcp_f32_e32 v176, v175
	s_nop 0
	v_fma_f32 v177, -v175, v176, 1.0
	v_fmac_f32_e32 v176, v177, v176
	v_div_scale_f32 v177, vcc, s11, v221, s11
	v_mul_f32_e32 v178, v177, v176
	v_fma_f32 v180, -v175, v178, v177
	v_fmac_f32_e32 v178, v180, v176
	v_fma_f32 v175, -v175, v178, v177
	s_nop 0
	v_div_fmas_f32 v175, v175, v176, v178
	v_div_fixup_f32 v175, v175, v221, s11
	v_cmp_lt_f32_e32 vcc, 0, v221
	s_nop 1
	v_cndmask_b32_e32 v227, 0, v175, vcc
	v_div_scale_f32 v175, s[58:59], v222, v222, s11
	v_rcp_f32_e32 v176, v175
	s_nop 0
	v_fma_f32 v177, -v175, v176, 1.0
	v_fmac_f32_e32 v176, v177, v176
	v_div_scale_f32 v177, vcc, s11, v222, s11
	v_mul_f32_e32 v178, v177, v176
	v_fma_f32 v180, -v175, v178, v177
	v_fmac_f32_e32 v178, v180, v176
	v_fma_f32 v175, -v175, v178, v177
	s_nop 0
	v_div_fmas_f32 v175, v175, v176, v178
	v_div_fixup_f32 v175, v175, v222, s11
	v_cmp_lt_f32_e32 vcc, 0, v222
	s_nop 1
	v_cndmask_b32_e32 v228, 0, v175, vcc
	v_div_scale_f32 v175, s[58:59], v223, v223, s11
	v_rcp_f32_e32 v176, v175
	s_nop 0
	v_fma_f32 v177, -v175, v176, 1.0
	v_fmac_f32_e32 v176, v177, v176
	v_div_scale_f32 v177, vcc, s11, v223, s11
	v_mul_f32_e32 v178, v177, v176
	v_fma_f32 v180, -v175, v178, v177
	v_fmac_f32_e32 v178, v180, v176
	v_fma_f32 v175, -v175, v178, v177
	s_nop 0
	v_div_fmas_f32 v175, v175, v176, v178
	v_div_fixup_f32 v175, v175, v223, s11
	v_cmp_lt_f32_e32 vcc, 0, v223
	s_nop 1
	v_cndmask_b32_e32 v229, 0, v175, vcc
	s_add_u32 s4, s0, s33
	s_lshl_b32 s3, s4, 6
	s_add_u32 s54, s52, s3
	s_addc_u32 s55, s53, 0
	v_mul_f32_e32 v186, v6, v226
	v_rndne_f32_e32 v186, v186
	v_cvt_i32_f32_e32 v186, v186
	v_mul_f32_e32 v187, v10, v226
	v_rndne_f32_e32 v187, v187
	v_cvt_i32_f32_e32 v187, v187
	v_mul_f32_e32 v188, v14, v226
	v_rndne_f32_e32 v188, v188
	v_cvt_i32_f32_e32 v188, v188
	v_mul_f32_e32 v189, v18, v226
	v_rndne_f32_e32 v189, v189
	v_cvt_i32_f32_e32 v189, v189
	v_and_b32_e32 v186, 0xff, v186
	v_and_b32_e32 v187, 0xff, v187
	v_and_b32_e32 v188, 0xff, v188
	v_lshl_or_b32 v190, v187, 8, v186
	v_lshl_or_b32 v190, v188, 16, v190
	v_lshl_or_b32 v190, v189, 24, v190
	ds_write_b32 v139, v190 offset:0
	v_mul_f32_e32 v186, v7, v227
	v_rndne_f32_e32 v186, v186
	v_cvt_i32_f32_e32 v186, v186
	v_mul_f32_e32 v187, v11, v227
	v_rndne_f32_e32 v187, v187
	v_cvt_i32_f32_e32 v187, v187
	v_mul_f32_e32 v188, v15, v227
	v_rndne_f32_e32 v188, v188
	v_cvt_i32_f32_e32 v188, v188
	v_mul_f32_e32 v189, v19, v227
	v_rndne_f32_e32 v189, v189
	v_cvt_i32_f32_e32 v189, v189
	v_and_b32_e32 v186, 0xff, v186
	v_and_b32_e32 v187, 0xff, v187
	v_and_b32_e32 v188, 0xff, v188
	v_lshl_or_b32 v190, v187, 8, v186
	v_lshl_or_b32 v190, v188, 16, v190
	v_lshl_or_b32 v190, v189, 24, v190
	ds_write_b32 v139, v190 offset:512
	v_mul_f32_e32 v186, v8, v228
	v_rndne_f32_e32 v186, v186
	v_cvt_i32_f32_e32 v186, v186
	v_mul_f32_e32 v187, v12, v228
	v_rndne_f32_e32 v187, v187
	v_cvt_i32_f32_e32 v187, v187
	v_mul_f32_e32 v188, v16, v228
	v_rndne_f32_e32 v188, v188
	v_cvt_i32_f32_e32 v188, v188
	v_mul_f32_e32 v189, v20, v228
	v_rndne_f32_e32 v189, v189
	v_cvt_i32_f32_e32 v189, v189
	v_and_b32_e32 v186, 0xff, v186
	v_and_b32_e32 v187, 0xff, v187
	v_and_b32_e32 v188, 0xff, v188
	v_lshl_or_b32 v190, v187, 8, v186
	v_lshl_or_b32 v190, v188, 16, v190
	v_lshl_or_b32 v190, v189, 24, v190
	ds_write_b32 v139, v190 offset:1024
	v_mul_f32_e32 v186, v9, v229
	v_rndne_f32_e32 v186, v186
	v_cvt_i32_f32_e32 v186, v186
	v_mul_f32_e32 v187, v13, v229
	v_rndne_f32_e32 v187, v187
	v_cvt_i32_f32_e32 v187, v187
	v_mul_f32_e32 v188, v17, v229
	v_rndne_f32_e32 v188, v188
	v_cvt_i32_f32_e32 v188, v188
	v_mul_f32_e32 v189, v21, v229
	v_rndne_f32_e32 v189, v189
	v_cvt_i32_f32_e32 v189, v189
	v_and_b32_e32 v186, 0xff, v186
	v_and_b32_e32 v187, 0xff, v187
	v_and_b32_e32 v188, 0xff, v188
	v_lshl_or_b32 v190, v187, 8, v186
	v_lshl_or_b32 v190, v188, 16, v190
	v_lshl_or_b32 v190, v189, 24, v190
	ds_write_b32 v139, v190 offset:1536
	s_cmp_ge_u32 s4, 0x560
	s_cbranch_scc1 .Lc16p3_ffn2_nopf_0
	global_load_dwordx4 v[6:9], v138, s[54:55]
	s_add_u32 s54, s54, 0x15800
	s_addc_u32 s55, s55, 0
	global_load_dwordx4 v[10:13], v138, s[54:55]
	s_add_u32 s54, s54, 0x15800
	s_addc_u32 s55, s55, 0
	global_load_dwordx4 v[14:17], v138, s[54:55]
	s_add_u32 s54, s54, 0x15800
	s_addc_u32 s55, s55, 0
	global_load_dwordx4 v[18:21], v138, s[54:55]
	s_add_u32 s54, s54, 0x51f800
	s_addc_u32 s55, s55, 0
.Lc16p3_ffn2_nopf_0:
	v_mul_f32_e32 v186, v22, v226
	v_rndne_f32_e32 v186, v186
	v_cvt_i32_f32_e32 v186, v186
	v_mul_f32_e32 v187, v26, v226
	v_rndne_f32_e32 v187, v187
	v_cvt_i32_f32_e32 v187, v187
	v_mul_f32_e32 v188, v30, v226
	v_rndne_f32_e32 v188, v188
	v_cvt_i32_f32_e32 v188, v188
	v_mul_f32_e32 v189, v34, v226
	v_rndne_f32_e32 v189, v189
	v_cvt_i32_f32_e32 v189, v189
	v_and_b32_e32 v186, 0xff, v186
	v_and_b32_e32 v187, 0xff, v187
	v_and_b32_e32 v188, 0xff, v188
	v_lshl_or_b32 v190, v187, 8, v186
	v_lshl_or_b32 v190, v188, 16, v190
	v_lshl_or_b32 v190, v189, 24, v190
	ds_write_b32 v139, v190 offset:64
	v_mul_f32_e32 v186, v23, v227
	v_rndne_f32_e32 v186, v186
	v_cvt_i32_f32_e32 v186, v186
	v_mul_f32_e32 v187, v27, v227
	v_rndne_f32_e32 v187, v187
	v_cvt_i32_f32_e32 v187, v187
	v_mul_f32_e32 v188, v31, v227
	v_rndne_f32_e32 v188, v188
	v_cvt_i32_f32_e32 v188, v188
	v_mul_f32_e32 v189, v35, v227
	v_rndne_f32_e32 v189, v189
	v_cvt_i32_f32_e32 v189, v189
	v_and_b32_e32 v186, 0xff, v186
	v_and_b32_e32 v187, 0xff, v187
	v_and_b32_e32 v188, 0xff, v188
	v_lshl_or_b32 v190, v187, 8, v186
	v_lshl_or_b32 v190, v188, 16, v190
	v_lshl_or_b32 v190, v189, 24, v190
	ds_write_b32 v139, v190 offset:576
	v_mul_f32_e32 v186, v24, v228
	v_rndne_f32_e32 v186, v186
	v_cvt_i32_f32_e32 v186, v186
	v_mul_f32_e32 v187, v28, v228
	v_rndne_f32_e32 v187, v187
	v_cvt_i32_f32_e32 v187, v187
	v_mul_f32_e32 v188, v32, v228
	v_rndne_f32_e32 v188, v188
	v_cvt_i32_f32_e32 v188, v188
	v_mul_f32_e32 v189, v36, v228
	v_rndne_f32_e32 v189, v189
	v_cvt_i32_f32_e32 v189, v189
	v_and_b32_e32 v186, 0xff, v186
	v_and_b32_e32 v187, 0xff, v187
	v_and_b32_e32 v188, 0xff, v188
	v_lshl_or_b32 v190, v187, 8, v186
	v_lshl_or_b32 v190, v188, 16, v190
	v_lshl_or_b32 v190, v189, 24, v190
	ds_write_b32 v139, v190 offset:1088
	v_mul_f32_e32 v186, v25, v229
	v_rndne_f32_e32 v186, v186
	v_cvt_i32_f32_e32 v186, v186
	v_mul_f32_e32 v187, v29, v229
	v_rndne_f32_e32 v187, v187
	v_cvt_i32_f32_e32 v187, v187
	v_mul_f32_e32 v188, v33, v229
	v_rndne_f32_e32 v188, v188
	v_cvt_i32_f32_e32 v188, v188
	v_mul_f32_e32 v189, v37, v229
	v_rndne_f32_e32 v189, v189
	v_cvt_i32_f32_e32 v189, v189
	v_and_b32_e32 v186, 0xff, v186
	v_and_b32_e32 v187, 0xff, v187
	v_and_b32_e32 v188, 0xff, v188
	v_lshl_or_b32 v190, v187, 8, v186
	v_lshl_or_b32 v190, v188, 16, v190
	v_lshl_or_b32 v190, v189, 24, v190
	ds_write_b32 v139, v190 offset:1600
	s_cmp_ge_u32 s4, 0x560
	s_cbranch_scc1 .Lc16p3_ffn2_nopf_1
	global_load_dwordx4 v[22:25], v138, s[54:55]
	s_add_u32 s54, s54, 0x15800
	s_addc_u32 s55, s55, 0
	global_load_dwordx4 v[26:29], v138, s[54:55]
	s_add_u32 s54, s54, 0x15800
	s_addc_u32 s55, s55, 0
	global_load_dwordx4 v[30:33], v138, s[54:55]
	s_add_u32 s54, s54, 0x15800
	s_addc_u32 s55, s55, 0
	global_load_dwordx4 v[34:37], v138, s[54:55]
	s_add_u32 s54, s54, 0x51f800
	s_addc_u32 s55, s55, 0
.Lc16p3_ffn2_nopf_1:
	v_mul_f32_e32 v186, v38, v226
	v_rndne_f32_e32 v186, v186
	v_cvt_i32_f32_e32 v186, v186
	v_mul_f32_e32 v187, v42, v226
	v_rndne_f32_e32 v187, v187
	v_cvt_i32_f32_e32 v187, v187
	v_mul_f32_e32 v188, v46, v226
	v_rndne_f32_e32 v188, v188
	v_cvt_i32_f32_e32 v188, v188
	v_mul_f32_e32 v189, v50, v226
	v_rndne_f32_e32 v189, v189
	v_cvt_i32_f32_e32 v189, v189
	v_and_b32_e32 v186, 0xff, v186
	v_and_b32_e32 v187, 0xff, v187
	v_and_b32_e32 v188, 0xff, v188
	v_lshl_or_b32 v190, v187, 8, v186
	v_lshl_or_b32 v190, v188, 16, v190
	v_lshl_or_b32 v190, v189, 24, v190
	ds_write_b32 v139, v190 offset:128
	v_mul_f32_e32 v186, v39, v227
	v_rndne_f32_e32 v186, v186
	v_cvt_i32_f32_e32 v186, v186
	v_mul_f32_e32 v187, v43, v227
	v_rndne_f32_e32 v187, v187
	v_cvt_i32_f32_e32 v187, v187
	v_mul_f32_e32 v188, v47, v227
	v_rndne_f32_e32 v188, v188
	v_cvt_i32_f32_e32 v188, v188
	v_mul_f32_e32 v189, v51, v227
	v_rndne_f32_e32 v189, v189
	v_cvt_i32_f32_e32 v189, v189
	v_and_b32_e32 v186, 0xff, v186
	v_and_b32_e32 v187, 0xff, v187
	v_and_b32_e32 v188, 0xff, v188
	v_lshl_or_b32 v190, v187, 8, v186
	v_lshl_or_b32 v190, v188, 16, v190
	v_lshl_or_b32 v190, v189, 24, v190
	ds_write_b32 v139, v190 offset:640
	v_mul_f32_e32 v186, v40, v228
	v_rndne_f32_e32 v186, v186
	v_cvt_i32_f32_e32 v186, v186
	v_mul_f32_e32 v187, v44, v228
	v_rndne_f32_e32 v187, v187
	v_cvt_i32_f32_e32 v187, v187
	v_mul_f32_e32 v188, v48, v228
	v_rndne_f32_e32 v188, v188
	v_cvt_i32_f32_e32 v188, v188
	v_mul_f32_e32 v189, v52, v228
	v_rndne_f32_e32 v189, v189
	v_cvt_i32_f32_e32 v189, v189
	v_and_b32_e32 v186, 0xff, v186
	v_and_b32_e32 v187, 0xff, v187
	v_and_b32_e32 v188, 0xff, v188
	v_lshl_or_b32 v190, v187, 8, v186
	v_lshl_or_b32 v190, v188, 16, v190
	v_lshl_or_b32 v190, v189, 24, v190
	ds_write_b32 v139, v190 offset:1152
	v_mul_f32_e32 v186, v41, v229
	v_rndne_f32_e32 v186, v186
	v_cvt_i32_f32_e32 v186, v186
	v_mul_f32_e32 v187, v45, v229
	v_rndne_f32_e32 v187, v187
	v_cvt_i32_f32_e32 v187, v187
	v_mul_f32_e32 v188, v49, v229
	v_rndne_f32_e32 v188, v188
	v_cvt_i32_f32_e32 v188, v188
	v_mul_f32_e32 v189, v53, v229
	v_rndne_f32_e32 v189, v189
	v_cvt_i32_f32_e32 v189, v189
	v_and_b32_e32 v186, 0xff, v186
	v_and_b32_e32 v187, 0xff, v187
	v_and_b32_e32 v188, 0xff, v188
	v_lshl_or_b32 v190, v187, 8, v186
	v_lshl_or_b32 v190, v188, 16, v190
	v_lshl_or_b32 v190, v189, 24, v190
	ds_write_b32 v139, v190 offset:1664
	s_cmp_ge_u32 s4, 0x560
	s_cbranch_scc1 .Lc16p3_ffn2_nopf_2
	global_load_dwordx4 v[38:41], v138, s[54:55]
	s_add_u32 s54, s54, 0x15800
	s_addc_u32 s55, s55, 0
	global_load_dwordx4 v[42:45], v138, s[54:55]
	s_add_u32 s54, s54, 0x15800
	s_addc_u32 s55, s55, 0
	global_load_dwordx4 v[46:49], v138, s[54:55]
	s_add_u32 s54, s54, 0x15800
	s_addc_u32 s55, s55, 0
	global_load_dwordx4 v[50:53], v138, s[54:55]
	s_add_u32 s54, s54, 0x51f800
	s_addc_u32 s55, s55, 0
.Lc16p3_ffn2_nopf_2:
	v_mul_f32_e32 v186, v54, v226
	v_rndne_f32_e32 v186, v186
	v_cvt_i32_f32_e32 v186, v186
	v_mul_f32_e32 v187, v58, v226
	v_rndne_f32_e32 v187, v187
	v_cvt_i32_f32_e32 v187, v187
	v_mul_f32_e32 v188, v62, v226
	v_rndne_f32_e32 v188, v188
	v_cvt_i32_f32_e32 v188, v188
	v_mul_f32_e32 v189, v66, v226
	v_rndne_f32_e32 v189, v189
	v_cvt_i32_f32_e32 v189, v189
	v_and_b32_e32 v186, 0xff, v186
	v_and_b32_e32 v187, 0xff, v187
	v_and_b32_e32 v188, 0xff, v188
	v_lshl_or_b32 v190, v187, 8, v186
	v_lshl_or_b32 v190, v188, 16, v190
	v_lshl_or_b32 v190, v189, 24, v190
	ds_write_b32 v139, v190 offset:192
	v_mul_f32_e32 v186, v55, v227
	v_rndne_f32_e32 v186, v186
	v_cvt_i32_f32_e32 v186, v186
	v_mul_f32_e32 v187, v59, v227
	v_rndne_f32_e32 v187, v187
	v_cvt_i32_f32_e32 v187, v187
	v_mul_f32_e32 v188, v63, v227
	v_rndne_f32_e32 v188, v188
	v_cvt_i32_f32_e32 v188, v188
	v_mul_f32_e32 v189, v67, v227
	v_rndne_f32_e32 v189, v189
	v_cvt_i32_f32_e32 v189, v189
	v_and_b32_e32 v186, 0xff, v186
	v_and_b32_e32 v187, 0xff, v187
	v_and_b32_e32 v188, 0xff, v188
	v_lshl_or_b32 v190, v187, 8, v186
	v_lshl_or_b32 v190, v188, 16, v190
	v_lshl_or_b32 v190, v189, 24, v190
	ds_write_b32 v139, v190 offset:704
	v_mul_f32_e32 v186, v56, v228
	v_rndne_f32_e32 v186, v186
	v_cvt_i32_f32_e32 v186, v186
	v_mul_f32_e32 v187, v60, v228
	v_rndne_f32_e32 v187, v187
	v_cvt_i32_f32_e32 v187, v187
	v_mul_f32_e32 v188, v64, v228
	v_rndne_f32_e32 v188, v188
	v_cvt_i32_f32_e32 v188, v188
	v_mul_f32_e32 v189, v68, v228
	v_rndne_f32_e32 v189, v189
	v_cvt_i32_f32_e32 v189, v189
	v_and_b32_e32 v186, 0xff, v186
	v_and_b32_e32 v187, 0xff, v187
	v_and_b32_e32 v188, 0xff, v188
	v_lshl_or_b32 v190, v187, 8, v186
	v_lshl_or_b32 v190, v188, 16, v190
	v_lshl_or_b32 v190, v189, 24, v190
	ds_write_b32 v139, v190 offset:1216
	v_mul_f32_e32 v186, v57, v229
	v_rndne_f32_e32 v186, v186
	v_cvt_i32_f32_e32 v186, v186
	v_mul_f32_e32 v187, v61, v229
	v_rndne_f32_e32 v187, v187
	v_cvt_i32_f32_e32 v187, v187
	v_mul_f32_e32 v188, v65, v229
	v_rndne_f32_e32 v188, v188
	v_cvt_i32_f32_e32 v188, v188
	v_mul_f32_e32 v189, v69, v229
	v_rndne_f32_e32 v189, v189
	v_cvt_i32_f32_e32 v189, v189
	v_and_b32_e32 v186, 0xff, v186
	v_and_b32_e32 v187, 0xff, v187
	v_and_b32_e32 v188, 0xff, v188
	v_lshl_or_b32 v190, v187, 8, v186
	v_lshl_or_b32 v190, v188, 16, v190
	v_lshl_or_b32 v190, v189, 24, v190
	ds_write_b32 v139, v190 offset:1728
	s_cmp_ge_u32 s4, 0x560
	s_cbranch_scc1 .Lc16p3_ffn2_nopf_3
	global_load_dwordx4 v[54:57], v138, s[54:55]
	s_add_u32 s54, s54, 0x15800
	s_addc_u32 s55, s55, 0
	global_load_dwordx4 v[58:61], v138, s[54:55]
	s_add_u32 s54, s54, 0x15800
	s_addc_u32 s55, s55, 0
	global_load_dwordx4 v[62:65], v138, s[54:55]
	s_add_u32 s54, s54, 0x15800
	s_addc_u32 s55, s55, 0
	global_load_dwordx4 v[66:69], v138, s[54:55]
	s_add_u32 s54, s54, 0x51f800
	s_addc_u32 s55, s55, 0
.Lc16p3_ffn2_nopf_3:
	v_mul_f32_e32 v186, v70, v226
	v_rndne_f32_e32 v186, v186
	v_cvt_i32_f32_e32 v186, v186
	v_mul_f32_e32 v187, v74, v226
	v_rndne_f32_e32 v187, v187
	v_cvt_i32_f32_e32 v187, v187
	v_mul_f32_e32 v188, v78, v226
	v_rndne_f32_e32 v188, v188
	v_cvt_i32_f32_e32 v188, v188
	v_mul_f32_e32 v189, v82, v226
	v_rndne_f32_e32 v189, v189
	v_cvt_i32_f32_e32 v189, v189
	v_and_b32_e32 v186, 0xff, v186
	v_and_b32_e32 v187, 0xff, v187
	v_and_b32_e32 v188, 0xff, v188
	v_lshl_or_b32 v190, v187, 8, v186
	v_lshl_or_b32 v190, v188, 16, v190
	v_lshl_or_b32 v190, v189, 24, v190
	ds_write_b32 v139, v190 offset:256
	v_mul_f32_e32 v186, v71, v227
	v_rndne_f32_e32 v186, v186
	v_cvt_i32_f32_e32 v186, v186
	v_mul_f32_e32 v187, v75, v227
	v_rndne_f32_e32 v187, v187
	v_cvt_i32_f32_e32 v187, v187
	v_mul_f32_e32 v188, v79, v227
	v_rndne_f32_e32 v188, v188
	v_cvt_i32_f32_e32 v188, v188
	v_mul_f32_e32 v189, v83, v227
	v_rndne_f32_e32 v189, v189
	v_cvt_i32_f32_e32 v189, v189
	v_and_b32_e32 v186, 0xff, v186
	v_and_b32_e32 v187, 0xff, v187
	v_and_b32_e32 v188, 0xff, v188
	v_lshl_or_b32 v190, v187, 8, v186
	v_lshl_or_b32 v190, v188, 16, v190
	v_lshl_or_b32 v190, v189, 24, v190
	ds_write_b32 v139, v190 offset:768
	v_mul_f32_e32 v186, v72, v228
	v_rndne_f32_e32 v186, v186
	v_cvt_i32_f32_e32 v186, v186
	v_mul_f32_e32 v187, v76, v228
	v_rndne_f32_e32 v187, v187
	v_cvt_i32_f32_e32 v187, v187
	v_mul_f32_e32 v188, v80, v228
	v_rndne_f32_e32 v188, v188
	v_cvt_i32_f32_e32 v188, v188
	v_mul_f32_e32 v189, v84, v228
	v_rndne_f32_e32 v189, v189
	v_cvt_i32_f32_e32 v189, v189
	v_and_b32_e32 v186, 0xff, v186
	v_and_b32_e32 v187, 0xff, v187
	v_and_b32_e32 v188, 0xff, v188
	v_lshl_or_b32 v190, v187, 8, v186
	v_lshl_or_b32 v190, v188, 16, v190
	v_lshl_or_b32 v190, v189, 24, v190
	ds_write_b32 v139, v190 offset:1280
	v_mul_f32_e32 v186, v73, v229
	v_rndne_f32_e32 v186, v186
	v_cvt_i32_f32_e32 v186, v186
	v_mul_f32_e32 v187, v77, v229
	v_rndne_f32_e32 v187, v187
	v_cvt_i32_f32_e32 v187, v187
	v_mul_f32_e32 v188, v81, v229
	v_rndne_f32_e32 v188, v188
	v_cvt_i32_f32_e32 v188, v188
	v_mul_f32_e32 v189, v85, v229
	v_rndne_f32_e32 v189, v189
	v_cvt_i32_f32_e32 v189, v189
	v_and_b32_e32 v186, 0xff, v186
	v_and_b32_e32 v187, 0xff, v187
	v_and_b32_e32 v188, 0xff, v188
	v_lshl_or_b32 v190, v187, 8, v186
	v_lshl_or_b32 v190, v188, 16, v190
	v_lshl_or_b32 v190, v189, 24, v190
	ds_write_b32 v139, v190 offset:1792
	s_cmp_ge_u32 s4, 0x560
	s_cbranch_scc1 .Lc16p3_ffn2_nopf_4
	global_load_dwordx4 v[70:73], v138, s[54:55]
	s_add_u32 s54, s54, 0x15800
	s_addc_u32 s55, s55, 0
	global_load_dwordx4 v[74:77], v138, s[54:55]
	s_add_u32 s54, s54, 0x15800
	s_addc_u32 s55, s55, 0
	global_load_dwordx4 v[78:81], v138, s[54:55]
	s_add_u32 s54, s54, 0x15800
	s_addc_u32 s55, s55, 0
	global_load_dwordx4 v[82:85], v138, s[54:55]
	s_add_u32 s54, s54, 0x51f800
	s_addc_u32 s55, s55, 0
.Lc16p3_ffn2_nopf_4:
	v_mul_f32_e32 v186, v86, v226
	v_rndne_f32_e32 v186, v186
	v_cvt_i32_f32_e32 v186, v186
	v_mul_f32_e32 v187, v90, v226
	v_rndne_f32_e32 v187, v187
	v_cvt_i32_f32_e32 v187, v187
	v_mul_f32_e32 v188, v94, v226
	v_rndne_f32_e32 v188, v188
	v_cvt_i32_f32_e32 v188, v188
	v_mul_f32_e32 v189, v98, v226
	v_rndne_f32_e32 v189, v189
	v_cvt_i32_f32_e32 v189, v189
	v_and_b32_e32 v186, 0xff, v186
	v_and_b32_e32 v187, 0xff, v187
	v_and_b32_e32 v188, 0xff, v188
	v_lshl_or_b32 v190, v187, 8, v186
	v_lshl_or_b32 v190, v188, 16, v190
	v_lshl_or_b32 v190, v189, 24, v190
	ds_write_b32 v139, v190 offset:320
	v_mul_f32_e32 v186, v87, v227
	v_rndne_f32_e32 v186, v186
	v_cvt_i32_f32_e32 v186, v186
	v_mul_f32_e32 v187, v91, v227
	v_rndne_f32_e32 v187, v187
	v_cvt_i32_f32_e32 v187, v187
	v_mul_f32_e32 v188, v95, v227
	v_rndne_f32_e32 v188, v188
	v_cvt_i32_f32_e32 v188, v188
	v_mul_f32_e32 v189, v99, v227
	v_rndne_f32_e32 v189, v189
	v_cvt_i32_f32_e32 v189, v189
	v_and_b32_e32 v186, 0xff, v186
	v_and_b32_e32 v187, 0xff, v187
	v_and_b32_e32 v188, 0xff, v188
	v_lshl_or_b32 v190, v187, 8, v186
	v_lshl_or_b32 v190, v188, 16, v190
	v_lshl_or_b32 v190, v189, 24, v190
	ds_write_b32 v139, v190 offset:832
	v_mul_f32_e32 v186, v88, v228
	v_rndne_f32_e32 v186, v186
	v_cvt_i32_f32_e32 v186, v186
	v_mul_f32_e32 v187, v92, v228
	v_rndne_f32_e32 v187, v187
	v_cvt_i32_f32_e32 v187, v187
	v_mul_f32_e32 v188, v96, v228
	v_rndne_f32_e32 v188, v188
	v_cvt_i32_f32_e32 v188, v188
	v_mul_f32_e32 v189, v100, v228
	v_rndne_f32_e32 v189, v189
	v_cvt_i32_f32_e32 v189, v189
	v_and_b32_e32 v186, 0xff, v186
	v_and_b32_e32 v187, 0xff, v187
	v_and_b32_e32 v188, 0xff, v188
	v_lshl_or_b32 v190, v187, 8, v186
	v_lshl_or_b32 v190, v188, 16, v190
	v_lshl_or_b32 v190, v189, 24, v190
	ds_write_b32 v139, v190 offset:1344
	v_mul_f32_e32 v186, v89, v229
	v_rndne_f32_e32 v186, v186
	v_cvt_i32_f32_e32 v186, v186
	v_mul_f32_e32 v187, v93, v229
	v_rndne_f32_e32 v187, v187
	v_cvt_i32_f32_e32 v187, v187
	v_mul_f32_e32 v188, v97, v229
	v_rndne_f32_e32 v188, v188
	v_cvt_i32_f32_e32 v188, v188
	v_mul_f32_e32 v189, v101, v229
	v_rndne_f32_e32 v189, v189
	v_cvt_i32_f32_e32 v189, v189
	v_and_b32_e32 v186, 0xff, v186
	v_and_b32_e32 v187, 0xff, v187
	v_and_b32_e32 v188, 0xff, v188
	v_lshl_or_b32 v190, v187, 8, v186
	v_lshl_or_b32 v190, v188, 16, v190
	v_lshl_or_b32 v190, v189, 24, v190
	ds_write_b32 v139, v190 offset:1856
	s_cmp_ge_u32 s4, 0x560
	s_cbranch_scc1 .Lc16p3_ffn2_nopf_5
	global_load_dwordx4 v[86:89], v138, s[54:55]
	s_add_u32 s54, s54, 0x15800
	s_addc_u32 s55, s55, 0
	global_load_dwordx4 v[90:93], v138, s[54:55]
	s_add_u32 s54, s54, 0x15800
	s_addc_u32 s55, s55, 0
	global_load_dwordx4 v[94:97], v138, s[54:55]
	s_add_u32 s54, s54, 0x15800
	s_addc_u32 s55, s55, 0
	global_load_dwordx4 v[98:101], v138, s[54:55]
	s_add_u32 s54, s54, 0x51f800
	s_addc_u32 s55, s55, 0
.Lc16p3_ffn2_nopf_5:
	v_mul_f32_e32 v186, v102, v226
	v_rndne_f32_e32 v186, v186
	v_cvt_i32_f32_e32 v186, v186
	v_mul_f32_e32 v187, v106, v226
	v_rndne_f32_e32 v187, v187
	v_cvt_i32_f32_e32 v187, v187
	v_mul_f32_e32 v188, v110, v226
	v_rndne_f32_e32 v188, v188
	v_cvt_i32_f32_e32 v188, v188
	v_mul_f32_e32 v189, v114, v226
	v_rndne_f32_e32 v189, v189
	v_cvt_i32_f32_e32 v189, v189
	v_and_b32_e32 v186, 0xff, v186
	v_and_b32_e32 v187, 0xff, v187
	v_and_b32_e32 v188, 0xff, v188
	v_lshl_or_b32 v190, v187, 8, v186
	v_lshl_or_b32 v190, v188, 16, v190
	v_lshl_or_b32 v190, v189, 24, v190
	ds_write_b32 v139, v190 offset:384
	v_mul_f32_e32 v186, v103, v227
	v_rndne_f32_e32 v186, v186
	v_cvt_i32_f32_e32 v186, v186
	v_mul_f32_e32 v187, v107, v227
	v_rndne_f32_e32 v187, v187
	v_cvt_i32_f32_e32 v187, v187
	v_mul_f32_e32 v188, v111, v227
	v_rndne_f32_e32 v188, v188
	v_cvt_i32_f32_e32 v188, v188
	v_mul_f32_e32 v189, v115, v227
	v_rndne_f32_e32 v189, v189
	v_cvt_i32_f32_e32 v189, v189
	v_and_b32_e32 v186, 0xff, v186
	v_and_b32_e32 v187, 0xff, v187
	v_and_b32_e32 v188, 0xff, v188
	v_lshl_or_b32 v190, v187, 8, v186
	v_lshl_or_b32 v190, v188, 16, v190
	v_lshl_or_b32 v190, v189, 24, v190
	ds_write_b32 v139, v190 offset:896
	v_mul_f32_e32 v186, v104, v228
	v_rndne_f32_e32 v186, v186
	v_cvt_i32_f32_e32 v186, v186
	v_mul_f32_e32 v187, v108, v228
	v_rndne_f32_e32 v187, v187
	v_cvt_i32_f32_e32 v187, v187
	v_mul_f32_e32 v188, v112, v228
	v_rndne_f32_e32 v188, v188
	v_cvt_i32_f32_e32 v188, v188
	v_mul_f32_e32 v189, v116, v228
	v_rndne_f32_e32 v189, v189
	v_cvt_i32_f32_e32 v189, v189
	v_and_b32_e32 v186, 0xff, v186
	v_and_b32_e32 v187, 0xff, v187
	v_and_b32_e32 v188, 0xff, v188
	v_lshl_or_b32 v190, v187, 8, v186
	v_lshl_or_b32 v190, v188, 16, v190
	v_lshl_or_b32 v190, v189, 24, v190
	ds_write_b32 v139, v190 offset:1408
	v_mul_f32_e32 v186, v105, v229
	v_rndne_f32_e32 v186, v186
	v_cvt_i32_f32_e32 v186, v186
	v_mul_f32_e32 v187, v109, v229
	v_rndne_f32_e32 v187, v187
	v_cvt_i32_f32_e32 v187, v187
	v_mul_f32_e32 v188, v113, v229
	v_rndne_f32_e32 v188, v188
	v_cvt_i32_f32_e32 v188, v188
	v_mul_f32_e32 v189, v117, v229
	v_rndne_f32_e32 v189, v189
	v_cvt_i32_f32_e32 v189, v189
	v_and_b32_e32 v186, 0xff, v186
	v_and_b32_e32 v187, 0xff, v187
	v_and_b32_e32 v188, 0xff, v188
	v_lshl_or_b32 v190, v187, 8, v186
	v_lshl_or_b32 v190, v188, 16, v190
	v_lshl_or_b32 v190, v189, 24, v190
	ds_write_b32 v139, v190 offset:1920
	s_cmp_ge_u32 s4, 0x560
	s_cbranch_scc1 .Lc16p3_ffn2_nopf_6
	global_load_dwordx4 v[102:105], v138, s[54:55]
	s_add_u32 s54, s54, 0x15800
	s_addc_u32 s55, s55, 0
	global_load_dwordx4 v[106:109], v138, s[54:55]
	s_add_u32 s54, s54, 0x15800
	s_addc_u32 s55, s55, 0
	global_load_dwordx4 v[110:113], v138, s[54:55]
	s_add_u32 s54, s54, 0x15800
	s_addc_u32 s55, s55, 0
	global_load_dwordx4 v[114:117], v138, s[54:55]
	s_add_u32 s54, s54, 0x51f800
	s_addc_u32 s55, s55, 0
.Lc16p3_ffn2_nopf_6:
	v_mul_f32_e32 v186, v118, v226
	v_rndne_f32_e32 v186, v186
	v_cvt_i32_f32_e32 v186, v186
	v_mul_f32_e32 v187, v122, v226
	v_rndne_f32_e32 v187, v187
	v_cvt_i32_f32_e32 v187, v187
	v_mul_f32_e32 v188, v126, v226
	v_rndne_f32_e32 v188, v188
	v_cvt_i32_f32_e32 v188, v188
	v_mul_f32_e32 v189, v130, v226
	v_rndne_f32_e32 v189, v189
	v_cvt_i32_f32_e32 v189, v189
	v_and_b32_e32 v186, 0xff, v186
	v_and_b32_e32 v187, 0xff, v187
	v_and_b32_e32 v188, 0xff, v188
	v_lshl_or_b32 v190, v187, 8, v186
	v_lshl_or_b32 v190, v188, 16, v190
	v_lshl_or_b32 v190, v189, 24, v190
	ds_write_b32 v139, v190 offset:448
	v_mul_f32_e32 v186, v119, v227
	v_rndne_f32_e32 v186, v186
	v_cvt_i32_f32_e32 v186, v186
	v_mul_f32_e32 v187, v123, v227
	v_rndne_f32_e32 v187, v187
	v_cvt_i32_f32_e32 v187, v187
	v_mul_f32_e32 v188, v127, v227
	v_rndne_f32_e32 v188, v188
	v_cvt_i32_f32_e32 v188, v188
	v_mul_f32_e32 v189, v131, v227
	v_rndne_f32_e32 v189, v189
	v_cvt_i32_f32_e32 v189, v189
	v_and_b32_e32 v186, 0xff, v186
	v_and_b32_e32 v187, 0xff, v187
	v_and_b32_e32 v188, 0xff, v188
	v_lshl_or_b32 v190, v187, 8, v186
	v_lshl_or_b32 v190, v188, 16, v190
	v_lshl_or_b32 v190, v189, 24, v190
	ds_write_b32 v139, v190 offset:960
	v_mul_f32_e32 v186, v120, v228
	v_rndne_f32_e32 v186, v186
	v_cvt_i32_f32_e32 v186, v186
	v_mul_f32_e32 v187, v124, v228
	v_rndne_f32_e32 v187, v187
	v_cvt_i32_f32_e32 v187, v187
	v_mul_f32_e32 v188, v128, v228
	v_rndne_f32_e32 v188, v188
	v_cvt_i32_f32_e32 v188, v188
	v_mul_f32_e32 v189, v132, v228
	v_rndne_f32_e32 v189, v189
	v_cvt_i32_f32_e32 v189, v189
	v_and_b32_e32 v186, 0xff, v186
	v_and_b32_e32 v187, 0xff, v187
	v_and_b32_e32 v188, 0xff, v188
	v_lshl_or_b32 v190, v187, 8, v186
	v_lshl_or_b32 v190, v188, 16, v190
	v_lshl_or_b32 v190, v189, 24, v190
	ds_write_b32 v139, v190 offset:1472
	v_mul_f32_e32 v186, v121, v229
	v_rndne_f32_e32 v186, v186
	v_cvt_i32_f32_e32 v186, v186
	v_mul_f32_e32 v187, v125, v229
	v_rndne_f32_e32 v187, v187
	v_cvt_i32_f32_e32 v187, v187
	v_mul_f32_e32 v188, v129, v229
	v_rndne_f32_e32 v188, v188
	v_cvt_i32_f32_e32 v188, v188
	v_mul_f32_e32 v189, v133, v229
	v_rndne_f32_e32 v189, v189
	v_cvt_i32_f32_e32 v189, v189
	v_and_b32_e32 v186, 0xff, v186
	v_and_b32_e32 v187, 0xff, v187
	v_and_b32_e32 v188, 0xff, v188
	v_lshl_or_b32 v190, v187, 8, v186
	v_lshl_or_b32 v190, v188, 16, v190
	v_lshl_or_b32 v190, v189, 24, v190
	ds_write_b32 v139, v190 offset:1984
	s_cmp_ge_u32 s4, 0x560
	s_cbranch_scc1 .Lc16p3_ffn2_nopf_7
	global_load_dwordx4 v[118:121], v138, s[54:55]
	s_add_u32 s54, s54, 0x15800
	s_addc_u32 s55, s55, 0
	global_load_dwordx4 v[122:125], v138, s[54:55]
	s_add_u32 s54, s54, 0x15800
	s_addc_u32 s55, s55, 0
	global_load_dwordx4 v[126:129], v138, s[54:55]
	s_add_u32 s54, s54, 0x15800
	s_addc_u32 s55, s55, 0
	global_load_dwordx4 v[130:133], v138, s[54:55]
